# K-loop s_setprio toggles removed (7 big GEMM loops) on top of v021
# speedup vs baseline: 1.0239x; 1.0080x over previous
; #define PG8_STAGE(bufoff, gbase, voff) do { _Pragma("unroll") for (int _i = 0; _i < 2; ++_i) \
;         __builtin_amdgcn_global_load_lds((const unsigned*)((const char*)(gbase) + (voff)[_i]), (LAS unsigned*)(lds + (bufoff) + ldsw + _i * 8192), 16, 0, 0); } while (0)
; #define PG8_LDA(dst, b, h) do { _Pragma("unroll") for (int m = 0; m < 4; ++m) _Pragma("unroll") for (int k = 0; k < 2; ++k) dst[m][k] = *(const LAS bf16x8*)(lds + PG8_SA(b, h) + aoff + m * 2048 + k * 1024); } while (0)
; #define PG8_LDB(dst, b, h) do { _Pragma("unroll") for (int n = 0; n < 2; ++n) _Pragma("unroll") for (int k = 0; k < 2; ++k) dst[n][k] = *(const LAS bf16x8*)(lds + PG8_SB(b, h) + boff + n * 2048 + k * 1024); } while (0)
; #define PG8_MMA(ai, bj, At, Bt) do { __builtin_amdgcn_s_setprio(1); _Pragma("unroll") for (int m = 0; m < 4; ++m) _Pragma("unroll") for (int n = 0; n < 2; ++n) _Pragma("unroll") for (int k = 0; k < 2; ++k) \
;         acc[ai][bj][m][n] = __builtin_amdgcn_mfma_f32_16x16x32_bf16(Bt[n][k], At[m][k], acc[ai][bj][m][n], 0, 0, 0); __builtin_amdgcn_s_setprio(0); } while (0)
; #define PG8_WAIT_V(n) asm volatile("s_waitcnt vmcnt(" #n ")" ::: "memory")
; #define PG8_WAIT_L(n) asm volatile("s_waitcnt lgkmcnt(" #n ")" ::: "memory")
; #define PG8_BAR __builtin_amdgcn_s_barrier()
; template <bool ALIGN_EPI, class Epi, class Sched>
; __device__ __forceinline__ void gemm_phase(LAS unsigned char* lds, const int lda, const int ldb, const int K, const Sched& S, const Epi& E, const size_t kstepA = (size_t)(BK * 2), const size_t kstepB = (size_t)(BK * 2)) {
;     ...
;             const bool last = (t == nt - 2);
;             const char* a1 = cA + (size_t)(t + 1) * kstepA;
;             const char* a2 = last ? nA : cA + (size_t)(t + 2) * kstepA; const char* b2 = last ? nB : cB + (size_t)(t + 2) * kstep;
;             const char* a3 = a2 + kstepA; const char* b3 = b2 + kstep;
;             PG8_LDB(B0, 0, 0); PG8_LDB(B1, 0, 1); PG8_SCHED; PG8_LDA(At, 0, 0); PG8_STAGE(PG8_SA(1, 1), a1 + hstepA, voffA);
;             PG8_WAIT_V(8); PG8_WAIT_L(0); PG8_BAR; PG8_MMA(0, 0, At, B0); PG8_MMA(0, 1, At, B1); PG8_BAR; PG8_SCHED;
;             PG8_LDA(At, 0, 1); PG8_STAGE(PG8_SB(0, 0), b2, voffB); PG8_STAGE(PG8_SB(0, 1), b2 + hstepB, voffB); PG8_STAGE(PG8_SA(0, 0), a2, voffA);
;             PG8_WAIT_V(8); PG8_WAIT_L(0); PG8_BAR; PG8_MMA(1, 0, At, B0); PG8_MMA(1, 1, At, B1); PG8_BAR; PG8_SCHED;
.LBB0_139:
	ds_read_b128 v[154:157], v150
	ds_read_b128 v[158:161], v150 offset:1024
	ds_read_b128 v[162:165], v150 offset:2048
	ds_read_b128 v[166:169], v150 offset:3072
	ds_read_b128 v[170:173], v151
	ds_read_b128 v[174:177], v151 offset:1024
	ds_read_b128 v[178:181], v151 offset:2048
	ds_read_b128 v[194:197], v151 offset:3072
	s_add_u32 s54, s70, 0x1fc000
	s_addc_u32 s55, s71, 0
	s_cmp_eq_u32 s51, 28
	s_cselect_b32 s78, s6, s54
	s_cselect_b32 s79, s7, s55
	s_cselect_b32 s76, s68, s41
	s_cselect_b32 s77, s69, s49
	s_add_u32 s74, s78, 0x200000
	s_addc_u32 s75, s79, 0
	s_add_i32 m0, s20, 0xc000
	ds_read_b128 v[198:201], v152
	ds_read_b128 v[202:205], v152 offset:1024
	ds_read_b128 v[206:209], v152 offset:2048
	ds_read_b128 v[210:213], v152 offset:3072
	ds_read_b128 v[214:217], v152 offset:4096
	ds_read_b128 v[218:221], v152 offset:5120
	ds_read_b128 v[222:225], v152 offset:6144
	ds_read_b128 v[226:229], v152 offset:7168
	global_load_lds_dwordx4 v138, s[70:71]
	s_add_i32 m0, s20, 0xe000
	s_nop 0
	global_load_lds_dwordx4 v140, s[70:71]
	s_waitcnt vmcnt(8)
	s_waitcnt lgkmcnt(0)
	s_barrier
	s_waitcnt lgkmcnt(0)
	v_mfma_f32_16x16x32_bf16 v[124:127], v[154:157], v[198:201], v[124:127]
	v_mfma_f32_16x16x32_bf16 v[124:127], v[158:161], v[202:205], v[124:127]
	v_mfma_f32_16x16x32_bf16 v[116:119], v[162:165], v[198:201], v[116:119]
	v_mfma_f32_16x16x32_bf16 v[116:119], v[166:169], v[202:205], v[116:119]
	v_mfma_f32_16x16x32_bf16 v[108:111], v[154:157], v[206:209], v[108:111]
	v_mfma_f32_16x16x32_bf16 v[108:111], v[158:161], v[210:213], v[108:111]
	v_mfma_f32_16x16x32_bf16 v[100:103], v[162:165], v[206:209], v[100:103]
	v_mfma_f32_16x16x32_bf16 v[100:103], v[166:169], v[210:213], v[100:103]
	v_mfma_f32_16x16x32_bf16 v[92:95], v[154:157], v[214:217], v[92:95]
	v_mfma_f32_16x16x32_bf16 v[92:95], v[158:161], v[218:221], v[92:95]
	v_mfma_f32_16x16x32_bf16 v[84:87], v[162:165], v[214:217], v[84:87]
	v_mfma_f32_16x16x32_bf16 v[84:87], v[166:169], v[218:221], v[84:87]
	v_mfma_f32_16x16x32_bf16 v[76:79], v[154:157], v[222:225], v[76:79]
	v_mfma_f32_16x16x32_bf16 v[76:79], v[158:161], v[226:229], v[76:79]
	v_mfma_f32_16x16x32_bf16 v[68:71], v[162:165], v[222:225], v[68:71]
	v_mfma_f32_16x16x32_bf16 v[68:71], v[166:169], v[226:229], v[68:71]
	v_mfma_f32_16x16x32_bf16 v[120:123], v[170:173], v[198:201], v[120:123]
	v_mfma_f32_16x16x32_bf16 v[120:123], v[174:177], v[202:205], v[120:123]
	v_mfma_f32_16x16x32_bf16 v[112:115], v[178:181], v[198:201], v[112:115]
	v_mfma_f32_16x16x32_bf16 v[112:115], v[194:197], v[202:205], v[112:115]
	v_mfma_f32_16x16x32_bf16 v[104:107], v[170:173], v[206:209], v[104:107]
	v_mfma_f32_16x16x32_bf16 v[104:107], v[174:177], v[210:213], v[104:107]
	v_mfma_f32_16x16x32_bf16 v[96:99], v[178:181], v[206:209], v[96:99]
	v_mfma_f32_16x16x32_bf16 v[96:99], v[194:197], v[210:213], v[96:99]
	v_mfma_f32_16x16x32_bf16 v[88:91], v[170:173], v[214:217], v[88:91]
	v_mfma_f32_16x16x32_bf16 v[88:91], v[174:177], v[218:221], v[88:91]
	v_mfma_f32_16x16x32_bf16 v[80:83], v[178:181], v[214:217], v[80:83]
	v_mfma_f32_16x16x32_bf16 v[80:83], v[194:197], v[218:221], v[80:83]
	v_mfma_f32_16x16x32_bf16 v[72:75], v[170:173], v[222:225], v[72:75]
	v_mfma_f32_16x16x32_bf16 v[72:75], v[174:177], v[226:229], v[72:75]
	v_mfma_f32_16x16x32_bf16 v[64:67], v[178:181], v[222:225], v[64:67]
	v_mfma_f32_16x16x32_bf16 v[64:67], v[194:197], v[226:229], v[64:67]
	s_barrier
	s_add_i32 s54, s42, s18
	s_mov_b32 m0, s54
	ds_read_b128 v[198:201], v152 offset:16384
	ds_read_b128 v[202:205], v152 offset:17408
	ds_read_b128 v[206:209], v152 offset:18432
	ds_read_b128 v[210:213], v152 offset:19456
	ds_read_b128 v[214:217], v152 offset:20480
	ds_read_b128 v[218:221], v152 offset:21504
	ds_read_b128 v[222:225], v152 offset:22528
	ds_read_b128 v[226:229], v152 offset:23552
	global_load_lds_dwordx4 v132, s[76:77]
	s_add_i32 m0, s54, 0x2000
	s_add_u32 s54, s76, 0x4000
	s_addc_u32 s55, s77, 0
	s_add_i32 s56, s43, s18
	global_load_lds_dwordx4 v128, s[76:77]
	s_mov_b32 m0, s56
	s_nop 0
	global_load_lds_dwordx4 v132, s[54:55]
	s_add_i32 m0, s56, 0x2000
	s_nop 0
	global_load_lds_dwordx4 v128, s[54:55]
	s_mov_b32 m0, s20
	s_nop 0
	global_load_lds_dwordx4 v134, s[78:79]
	s_mov_b32 m0, s21
	s_nop 0
	global_load_lds_dwordx4 v130, s[78:79]
	s_waitcnt vmcnt(8)
	s_waitcnt lgkmcnt(0)
	s_barrier
	s_waitcnt lgkmcnt(0)
	v_mfma_f32_16x16x32_bf16 v[60:63], v[154:157], v[198:201], v[60:63]
	v_mfma_f32_16x16x32_bf16 v[60:63], v[158:161], v[202:205], v[60:63]
	v_mfma_f32_16x16x32_bf16 v[52:55], v[162:165], v[198:201], v[52:55]
	v_mfma_f32_16x16x32_bf16 v[52:55], v[166:169], v[202:205], v[52:55]
	v_mfma_f32_16x16x32_bf16 v[44:47], v[154:157], v[206:209], v[44:47]
	v_mfma_f32_16x16x32_bf16 v[44:47], v[158:161], v[210:213], v[44:47]
	v_mfma_f32_16x16x32_bf16 v[36:39], v[162:165], v[206:209], v[36:39]
	v_mfma_f32_16x16x32_bf16 v[36:39], v[166:169], v[210:213], v[36:39]
	v_mfma_f32_16x16x32_bf16 v[28:31], v[154:157], v[214:217], v[28:31]
	v_mfma_f32_16x16x32_bf16 v[28:31], v[158:161], v[218:221], v[28:31]
	v_mfma_f32_16x16x32_bf16 v[20:23], v[162:165], v[214:217], v[20:23]
	v_mfma_f32_16x16x32_bf16 v[20:23], v[166:169], v[218:221], v[20:23]
	v_mfma_f32_16x16x32_bf16 v[12:15], v[154:157], v[222:225], v[12:15]
	v_mfma_f32_16x16x32_bf16 v[12:15], v[158:161], v[226:229], v[12:15]
	v_mfma_f32_16x16x32_bf16 v[4:7], v[162:165], v[222:225], v[4:7]
	v_mfma_f32_16x16x32_bf16 v[4:7], v[166:169], v[226:229], v[4:7]
	v_mfma_f32_16x16x32_bf16 v[56:59], v[170:173], v[198:201], v[56:59]
	v_mfma_f32_16x16x32_bf16 v[56:59], v[174:177], v[202:205], v[56:59]
	v_mfma_f32_16x16x32_bf16 v[48:51], v[178:181], v[198:201], v[48:51]
	v_mfma_f32_16x16x32_bf16 v[48:51], v[194:197], v[202:205], v[48:51]
	v_mfma_f32_16x16x32_bf16 v[40:43], v[170:173], v[206:209], v[40:43]
	v_mfma_f32_16x16x32_bf16 v[40:43], v[174:177], v[210:213], v[40:43]
	v_mfma_f32_16x16x32_bf16 v[32:35], v[178:181], v[206:209], v[32:35]
	v_mfma_f32_16x16x32_bf16 v[32:35], v[194:197], v[210:213], v[32:35]
	v_mfma_f32_16x16x32_bf16 v[24:27], v[170:173], v[214:217], v[24:27]
	v_mfma_f32_16x16x32_bf16 v[24:27], v[174:177], v[218:221], v[24:27]
	v_mfma_f32_16x16x32_bf16 v[16:19], v[178:181], v[214:217], v[16:19]
	v_mfma_f32_16x16x32_bf16 v[16:19], v[194:197], v[218:221], v[16:19]
	v_mfma_f32_16x16x32_bf16 v[8:11], v[170:173], v[222:225], v[8:11]
	v_mfma_f32_16x16x32_bf16 v[8:11], v[174:177], v[226:229], v[8:11]
	v_mfma_f32_16x16x32_bf16 v[0:3], v[178:181], v[222:225], v[0:3]
	v_mfma_f32_16x16x32_bf16 v[0:3], v[194:197], v[226:229], v[0:3]
	s_barrier
; #define PG8_STAGE(bufoff, gbase, voff) do { _Pragma("unroll") for (int _i = 0; _i < 2; ++_i) \
;         __builtin_amdgcn_global_load_lds((const unsigned*)((const char*)(gbase) + (voff)[_i]), (LAS unsigned*)(lds + (bufoff) + ldsw + _i * 8192), 16, 0, 0); } while (0)
; #define PG8_LDA(dst, b, h) do { _Pragma("unroll") for (int m = 0; m < 4; ++m) _Pragma("unroll") for (int k = 0; k < 2; ++k) dst[m][k] = *(const LAS bf16x8*)(lds + PG8_SA(b, h) + aoff + m * 2048 + k * 1024); } while (0)
; #define PG8_LDB(dst, b, h) do { _Pragma("unroll") for (int n = 0; n < 2; ++n) _Pragma("unroll") for (int k = 0; k < 2; ++k) dst[n][k] = *(const LAS bf16x8*)(lds + PG8_SB(b, h) + boff + n * 2048 + k * 1024); } while (0)
; #define PG8_MMA(ai, bj, At, Bt) do { __builtin_amdgcn_s_setprio(1); _Pragma("unroll") for (int m = 0; m < 4; ++m) _Pragma("unroll") for (int n = 0; n < 2; ++n) _Pragma("unroll") for (int k = 0; k < 2; ++k) \
;         acc[ai][bj][m][n] = __builtin_amdgcn_mfma_f32_16x16x32_bf16(Bt[n][k], At[m][k], acc[ai][bj][m][n], 0, 0, 0); __builtin_amdgcn_s_setprio(0); } while (0)
; #define PG8_WAIT_V(n) asm volatile("s_waitcnt vmcnt(" #n ")" ::: "memory")
; #define PG8_WAIT_L(n) asm volatile("s_waitcnt lgkmcnt(" #n ")" ::: "memory")
; #define PG8_BAR __builtin_amdgcn_s_barrier()
; #define PG8_SCHED __builtin_amdgcn_sched_barrier(0)
; template <bool ALIGN_EPI, class Epi, class Sched>
; __device__ __forceinline__ void gemm_phase(LAS unsigned char* lds, const int lda, const int ldb, const int K, const Sched& S, const Epi& E, const size_t kstepA = (size_t)(BK * 2), const size_t kstepB = (size_t)(BK * 2)) {
;     ...
;             PG8_LDB(B0, 1, 0); PG8_LDB(B1, 1, 1); PG8_SCHED; PG8_LDA(At, 1, 0); PG8_STAGE(PG8_SA(0, 1), a2 + hstepA, voffA);
;             PG8_WAIT_V(8); PG8_WAIT_L(0); PG8_BAR; PG8_MMA(0, 0, At, B0); PG8_MMA(0, 1, At, B1); PG8_BAR; PG8_SCHED;
;             PG8_LDA(At, 1, 1); PG8_STAGE(PG8_SB(1, 0), b3, voffB); PG8_STAGE(PG8_SB(1, 1), b3 + hstepB, voffB); PG8_STAGE(PG8_SA(1, 0), a3, voffA);
;             PG8_WAIT_V(8); PG8_WAIT_L(0); PG8_BAR; PG8_MMA(1, 0, At, B0); PG8_MMA(1, 1, At, B1); PG8_BAR; PG8_SCHED;
;         }
;         if constexpr (ALIGN_EPI) { if (wr == 0) PG8_BAR; }
	s_add_i32 s56, 0, 0x18000
	v_add_u32_e32 v146, s56, v149
	s_add_i32 s57, 0, 0x1c000
	ds_read_b128 v[154:157], v146
	ds_read_b128 v[158:161], v146 offset:1024
	ds_read_b128 v[162:165], v146 offset:2048
	ds_read_b128 v[166:169], v146 offset:3072
	v_add_u32_e32 v146, s57, v149
	ds_read_b128 v[170:173], v146
	ds_read_b128 v[174:177], v146 offset:1024
	ds_read_b128 v[178:181], v146 offset:2048
	ds_read_b128 v[194:197], v146 offset:3072
	s_add_u32 s54, s78, 0x4000
	s_addc_u32 s55, s79, 0
	s_mov_b32 m0, s22
	ds_read_b128 v[198:201], v152 offset:32768
	ds_read_b128 v[202:205], v152 offset:33792
	ds_read_b128 v[206:209], v152 offset:34816
	ds_read_b128 v[210:213], v152 offset:35840
	ds_read_b128 v[214:217], v152 offset:36864
	ds_read_b128 v[218:221], v152 offset:37888
	ds_read_b128 v[222:225], v152 offset:38912
	ds_read_b128 v[226:229], v152 offset:39936
	global_load_lds_dwordx4 v134, s[54:55]
	s_mov_b32 m0, s23
	s_nop 0
	global_load_lds_dwordx4 v130, s[54:55]
	s_waitcnt vmcnt(8)
	s_waitcnt lgkmcnt(0)
	s_barrier
	s_waitcnt lgkmcnt(0)
	v_mfma_f32_16x16x32_bf16 v[124:127], v[154:157], v[198:201], v[124:127]
	v_mfma_f32_16x16x32_bf16 v[124:127], v[158:161], v[202:205], v[124:127]
	v_mfma_f32_16x16x32_bf16 v[116:119], v[162:165], v[198:201], v[116:119]
	v_mfma_f32_16x16x32_bf16 v[116:119], v[166:169], v[202:205], v[116:119]
	v_mfma_f32_16x16x32_bf16 v[108:111], v[154:157], v[206:209], v[108:111]
	v_mfma_f32_16x16x32_bf16 v[108:111], v[158:161], v[210:213], v[108:111]
	v_mfma_f32_16x16x32_bf16 v[100:103], v[162:165], v[206:209], v[100:103]
	v_mfma_f32_16x16x32_bf16 v[100:103], v[166:169], v[210:213], v[100:103]
	v_mfma_f32_16x16x32_bf16 v[92:95], v[154:157], v[214:217], v[92:95]
	v_mfma_f32_16x16x32_bf16 v[92:95], v[158:161], v[218:221], v[92:95]
	v_mfma_f32_16x16x32_bf16 v[84:87], v[162:165], v[214:217], v[84:87]
	v_mfma_f32_16x16x32_bf16 v[84:87], v[166:169], v[218:221], v[84:87]
	v_mfma_f32_16x16x32_bf16 v[76:79], v[154:157], v[222:225], v[76:79]
	v_mfma_f32_16x16x32_bf16 v[76:79], v[158:161], v[226:229], v[76:79]
	v_mfma_f32_16x16x32_bf16 v[68:71], v[162:165], v[222:225], v[68:71]
	v_mfma_f32_16x16x32_bf16 v[68:71], v[166:169], v[226:229], v[68:71]
	v_mfma_f32_16x16x32_bf16 v[120:123], v[170:173], v[198:201], v[120:123]
	v_mfma_f32_16x16x32_bf16 v[120:123], v[174:177], v[202:205], v[120:123]
	v_mfma_f32_16x16x32_bf16 v[112:115], v[178:181], v[198:201], v[112:115]
	v_mfma_f32_16x16x32_bf16 v[112:115], v[194:197], v[202:205], v[112:115]
	v_mfma_f32_16x16x32_bf16 v[104:107], v[170:173], v[206:209], v[104:107]
	v_mfma_f32_16x16x32_bf16 v[104:107], v[174:177], v[210:213], v[104:107]
	v_mfma_f32_16x16x32_bf16 v[96:99], v[178:181], v[206:209], v[96:99]
	v_mfma_f32_16x16x32_bf16 v[96:99], v[194:197], v[210:213], v[96:99]
	v_mfma_f32_16x16x32_bf16 v[88:91], v[170:173], v[214:217], v[88:91]
	v_mfma_f32_16x16x32_bf16 v[88:91], v[174:177], v[218:221], v[88:91]
	v_mfma_f32_16x16x32_bf16 v[80:83], v[178:181], v[214:217], v[80:83]
	v_mfma_f32_16x16x32_bf16 v[80:83], v[194:197], v[218:221], v[80:83]
	v_mfma_f32_16x16x32_bf16 v[72:75], v[170:173], v[222:225], v[72:75]
	v_mfma_f32_16x16x32_bf16 v[72:75], v[174:177], v[226:229], v[72:75]
	v_mfma_f32_16x16x32_bf16 v[64:67], v[178:181], v[222:225], v[64:67]
	v_mfma_f32_16x16x32_bf16 v[64:67], v[194:197], v[226:229], v[64:67]
	s_barrier
	s_add_u32 s54, s76, 0x160000
	s_addc_u32 s55, s77, 0
	s_add_i32 s56, s56, s18
	s_mov_b32 m0, s56
	ds_read_b128 v[198:201], v152 offset:49152
	ds_read_b128 v[202:205], v152 offset:50176
	ds_read_b128 v[206:209], v152 offset:51200
	ds_read_b128 v[210:213], v152 offset:52224
	ds_read_b128 v[214:217], v152 offset:53248
	ds_read_b128 v[218:221], v152 offset:54272
	ds_read_b128 v[222:225], v152 offset:55296
	ds_read_b128 v[226:229], v152 offset:56320
	global_load_lds_dwordx4 v132, s[54:55]
	s_add_i32 m0, s56, 0x2000
	s_nop 0
	global_load_lds_dwordx4 v128, s[54:55]
	s_add_u32 s54, s76, 0x164000
	s_addc_u32 s55, s77, 0
	s_add_i32 s56, s57, s18
	s_mov_b32 m0, s56
	s_nop 0
	global_load_lds_dwordx4 v132, s[54:55]
	s_add_i32 m0, s56, 0x2000
	s_nop 0
	global_load_lds_dwordx4 v128, s[54:55]
	s_mov_b32 m0, s31
	s_nop 0
	global_load_lds_dwordx4 v134, s[74:75]
	s_mov_b32 m0, s33
	s_nop 0
	global_load_lds_dwordx4 v130, s[74:75]
	s_waitcnt vmcnt(8)
	s_waitcnt lgkmcnt(0)
	s_barrier
	s_waitcnt lgkmcnt(0)
	v_mfma_f32_16x16x32_bf16 v[60:63], v[154:157], v[198:201], v[60:63]
	v_mfma_f32_16x16x32_bf16 v[60:63], v[158:161], v[202:205], v[60:63]
	v_mfma_f32_16x16x32_bf16 v[52:55], v[162:165], v[198:201], v[52:55]
	v_mfma_f32_16x16x32_bf16 v[52:55], v[166:169], v[202:205], v[52:55]
	v_mfma_f32_16x16x32_bf16 v[44:47], v[154:157], v[206:209], v[44:47]
	v_mfma_f32_16x16x32_bf16 v[44:47], v[158:161], v[210:213], v[44:47]
	v_mfma_f32_16x16x32_bf16 v[36:39], v[162:165], v[206:209], v[36:39]
	v_mfma_f32_16x16x32_bf16 v[36:39], v[166:169], v[210:213], v[36:39]
	v_mfma_f32_16x16x32_bf16 v[28:31], v[154:157], v[214:217], v[28:31]
	v_mfma_f32_16x16x32_bf16 v[28:31], v[158:161], v[218:221], v[28:31]
	v_mfma_f32_16x16x32_bf16 v[20:23], v[162:165], v[214:217], v[20:23]
	v_mfma_f32_16x16x32_bf16 v[20:23], v[166:169], v[218:221], v[20:23]
	v_mfma_f32_16x16x32_bf16 v[12:15], v[154:157], v[222:225], v[12:15]
	v_mfma_f32_16x16x32_bf16 v[12:15], v[158:161], v[226:229], v[12:15]
	v_mfma_f32_16x16x32_bf16 v[4:7], v[162:165], v[222:225], v[4:7]
	v_mfma_f32_16x16x32_bf16 v[4:7], v[166:169], v[226:229], v[4:7]
	v_mfma_f32_16x16x32_bf16 v[56:59], v[170:173], v[198:201], v[56:59]
	v_mfma_f32_16x16x32_bf16 v[56:59], v[174:177], v[202:205], v[56:59]
	v_mfma_f32_16x16x32_bf16 v[48:51], v[178:181], v[198:201], v[48:51]
	v_mfma_f32_16x16x32_bf16 v[48:51], v[194:197], v[202:205], v[48:51]
	v_mfma_f32_16x16x32_bf16 v[40:43], v[170:173], v[206:209], v[40:43]
	v_mfma_f32_16x16x32_bf16 v[40:43], v[174:177], v[210:213], v[40:43]
	v_mfma_f32_16x16x32_bf16 v[32:35], v[178:181], v[206:209], v[32:35]
	v_mfma_f32_16x16x32_bf16 v[32:35], v[194:197], v[210:213], v[32:35]
	v_mfma_f32_16x16x32_bf16 v[24:27], v[170:173], v[214:217], v[24:27]
	v_mfma_f32_16x16x32_bf16 v[24:27], v[174:177], v[218:221], v[24:27]
	v_mfma_f32_16x16x32_bf16 v[16:19], v[178:181], v[214:217], v[16:19]
	v_mfma_f32_16x16x32_bf16 v[16:19], v[194:197], v[218:221], v[16:19]
	v_mfma_f32_16x16x32_bf16 v[8:11], v[170:173], v[222:225], v[8:11]
	v_mfma_f32_16x16x32_bf16 v[8:11], v[174:177], v[226:229], v[8:11]
	v_mfma_f32_16x16x32_bf16 v[0:3], v[178:181], v[222:225], v[0:3]
	v_mfma_f32_16x16x32_bf16 v[0:3], v[194:197], v[226:229], v[0:3]
	s_barrier
	s_add_i32 s51, s51, 2
	s_add_u32 s41, s41, 0x2c0000
	s_addc_u32 s49, s49, 0
	s_add_u32 s70, s70, 0x400000
	s_addc_u32 s71, s71, 0
	s_cmp_gt_u32 s51, 29
	s_cbranch_scc0 .LBB0_139
	s_and_b64 vcc, exec, s[12:13]
	s_cbranch_vccz .LBB0_142
	s_barrier

; #define PG8_STAGE(bufoff, gbase, voff) do { _Pragma("unroll") for (int _i = 0; _i < 2; ++_i) \
;         __builtin_amdgcn_global_load_lds((const unsigned*)((const char*)(gbase) + (voff)[_i]), (LAS unsigned*)(lds + (bufoff) + ldsw + _i * 8192), 16, 0, 0); } while (0)
; #define PG8_LDA(dst, b, h) do { _Pragma("unroll") for (int m = 0; m < 4; ++m) _Pragma("unroll") for (int k = 0; k < 2; ++k) dst[m][k] = *(const LAS bf16x8*)(lds + PG8_SA(b, h) + aoff + m * 2048 + k * 1024); } while (0)
; #define PG8_LDB(dst, b, h) do { _Pragma("unroll") for (int n = 0; n < 2; ++n) _Pragma("unroll") for (int k = 0; k < 2; ++k) dst[n][k] = *(const LAS bf16x8*)(lds + PG8_SB(b, h) + boff + n * 2048 + k * 1024); } while (0)
; #define PG8_MMA(ai, bj, At, Bt) do { __builtin_amdgcn_s_setprio(1); _Pragma("unroll") for (int m = 0; m < 4; ++m) _Pragma("unroll") for (int n = 0; n < 2; ++n) _Pragma("unroll") for (int k = 0; k < 2; ++k) \
;         acc[ai][bj][m][n] = __builtin_amdgcn_mfma_f32_16x16x32_bf16(Bt[n][k], At[m][k], acc[ai][bj][m][n], 0, 0, 0); __builtin_amdgcn_s_setprio(0); } while (0)
; #define PG8_WAIT_V(n) asm volatile("s_waitcnt vmcnt(" #n ")" ::: "memory")
; #define PG8_WAIT_L(n) asm volatile("s_waitcnt lgkmcnt(" #n ")" ::: "memory")
; #define PG8_BAR __builtin_amdgcn_s_barrier()
; template <bool ALIGN_EPI, class Epi, class Sched>
; __device__ __forceinline__ void gemm_phase(LAS unsigned char* lds, const int lda, const int ldb, const int K, const Sched& S, const Epi& E, const size_t kstepA = (size_t)(BK * 2), const size_t kstepB = (size_t)(BK * 2)) {
;     ...
;             const bool last = (t == nt - 2);
;             const char* a1 = cA + (size_t)(t + 1) * kstepA;
;             const char* a2 = last ? nA : cA + (size_t)(t + 2) * kstepA; const char* b2 = last ? nB : cB + (size_t)(t + 2) * kstep;
;             const char* a3 = a2 + kstepA; const char* b3 = b2 + kstep;
;             PG8_LDB(B0, 0, 0); PG8_LDB(B1, 0, 1); PG8_SCHED; PG8_LDA(At, 0, 0); PG8_STAGE(PG8_SA(1, 1), a1 + hstepA, voffA);
;             PG8_WAIT_V(8); PG8_WAIT_L(0); PG8_BAR; PG8_MMA(0, 0, At, B0); PG8_MMA(0, 1, At, B1); PG8_BAR; PG8_SCHED;
;             PG8_LDA(At, 0, 1); PG8_STAGE(PG8_SB(0, 0), b2, voffB); PG8_STAGE(PG8_SB(0, 1), b2 + hstepB, voffB); PG8_STAGE(PG8_SA(0, 0), a2, voffA);
;             PG8_WAIT_V(8); PG8_WAIT_L(0); PG8_BAR; PG8_MMA(1, 0, At, B0); PG8_MMA(1, 1, At, B1); PG8_BAR; PG8_SCHED;
.LBB0_218:
	ds_read_b128 v[64:67], v193
	ds_read_b128 v[68:71], v193 offset:1024
	ds_read_b128 v[80:83], v193 offset:2048
	ds_read_b128 v[84:87], v193 offset:3072
	ds_read_b128 v[144:147], v232
	ds_read_b128 v[148:151], v232 offset:1024
	ds_read_b128 v[152:155], v232 offset:2048
	ds_read_b128 v[156:159], v232 offset:3072
	s_add_u32 s54, s82, 0x1fc000
	s_addc_u32 s55, s83, 0
	s_cmpk_eq_i32 s51, 0x54
	s_cselect_b32 vcc_lo, s6, s54
	s_cselect_b32 vcc_hi, s7, s55
	s_cselect_b32 s96, s78, s13
	s_cselect_b32 s97, s79, s50
	s_add_u32 s94, vcc_lo, 0x200000
	s_addc_u32 s95, vcc_hi, 0
	s_add_i32 m0, s19, 0xc000
	ds_read_b128 v[160:163], v233
	ds_read_b128 v[164:167], v233 offset:1024
	ds_read_b128 v[168:171], v233 offset:2048
	ds_read_b128 v[172:175], v233 offset:3072
	ds_read_b128 v[176:179], v233 offset:4096
	ds_read_b128 v[180:183], v233 offset:5120
	ds_read_b128 v[212:215], v233 offset:6144
	ds_read_b128 v[216:219], v233 offset:7168
	global_load_lds_dwordx4 v204, s[82:83]
	s_add_i32 m0, s19, 0xe000
	s_nop 0
	global_load_lds_dwordx4 v206, s[82:83]
	s_waitcnt vmcnt(8)
	s_waitcnt lgkmcnt(0)
	s_barrier
	s_waitcnt lgkmcnt(0)
	v_mfma_f32_16x16x32_bf16 v[140:143], v[64:67], v[160:163], v[140:143]
	v_mfma_f32_16x16x32_bf16 v[140:143], v[68:71], v[164:167], v[140:143]
	v_mfma_f32_16x16x32_bf16 v[136:139], v[80:83], v[160:163], v[136:139]
	v_mfma_f32_16x16x32_bf16 v[136:139], v[84:87], v[164:167], v[136:139]
	v_mfma_f32_16x16x32_bf16 v[124:127], v[64:67], v[168:171], v[124:127]
	v_mfma_f32_16x16x32_bf16 v[124:127], v[68:71], v[172:175], v[124:127]
	v_mfma_f32_16x16x32_bf16 v[120:123], v[80:83], v[168:171], v[120:123]
	v_mfma_f32_16x16x32_bf16 v[120:123], v[84:87], v[172:175], v[120:123]
	v_mfma_f32_16x16x32_bf16 v[108:111], v[64:67], v[176:179], v[108:111]
	v_mfma_f32_16x16x32_bf16 v[108:111], v[68:71], v[180:183], v[108:111]
	v_mfma_f32_16x16x32_bf16 v[104:107], v[80:83], v[176:179], v[104:107]
	v_mfma_f32_16x16x32_bf16 v[104:107], v[84:87], v[180:183], v[104:107]
	v_mfma_f32_16x16x32_bf16 v[92:95], v[64:67], v[212:215], v[92:95]
	v_mfma_f32_16x16x32_bf16 v[92:95], v[68:71], v[216:219], v[92:95]
	v_mfma_f32_16x16x32_bf16 v[88:91], v[80:83], v[212:215], v[88:91]
	v_mfma_f32_16x16x32_bf16 v[88:91], v[84:87], v[216:219], v[88:91]
	v_mfma_f32_16x16x32_bf16 v[132:135], v[144:147], v[160:163], v[132:135]
	v_mfma_f32_16x16x32_bf16 v[132:135], v[148:151], v[164:167], v[132:135]
	v_mfma_f32_16x16x32_bf16 v[128:131], v[152:155], v[160:163], v[128:131]
	v_mfma_f32_16x16x32_bf16 v[128:131], v[156:159], v[164:167], v[128:131]
	v_mfma_f32_16x16x32_bf16 v[116:119], v[144:147], v[168:171], v[116:119]
	v_mfma_f32_16x16x32_bf16 v[116:119], v[148:151], v[172:175], v[116:119]
	v_mfma_f32_16x16x32_bf16 v[112:115], v[152:155], v[168:171], v[112:115]
	v_mfma_f32_16x16x32_bf16 v[112:115], v[156:159], v[172:175], v[112:115]
	v_mfma_f32_16x16x32_bf16 v[100:103], v[144:147], v[176:179], v[100:103]
	v_mfma_f32_16x16x32_bf16 v[100:103], v[148:151], v[180:183], v[100:103]
	v_mfma_f32_16x16x32_bf16 v[96:99], v[152:155], v[176:179], v[96:99]
	v_mfma_f32_16x16x32_bf16 v[96:99], v[156:159], v[180:183], v[96:99]
	v_mfma_f32_16x16x32_bf16 v[76:79], v[144:147], v[212:215], v[76:79]
	v_mfma_f32_16x16x32_bf16 v[76:79], v[148:151], v[216:219], v[76:79]
	v_mfma_f32_16x16x32_bf16 v[72:75], v[152:155], v[212:215], v[72:75]
	v_mfma_f32_16x16x32_bf16 v[72:75], v[156:159], v[216:219], v[72:75]
	s_barrier
	s_add_i32 s54, s33, s18
	s_mov_b32 m0, s54
	ds_read_b128 v[160:163], v233 offset:16384
	ds_read_b128 v[164:167], v233 offset:17408
	ds_read_b128 v[168:171], v233 offset:18432
	ds_read_b128 v[172:175], v233 offset:19456
	ds_read_b128 v[176:179], v233 offset:20480
	ds_read_b128 v[180:183], v233 offset:21504
	ds_read_b128 v[212:215], v233 offset:22528
	ds_read_b128 v[216:219], v233 offset:23552
	global_load_lds_dwordx4 v196, s[96:97]
	s_add_i32 m0, s54, 0x2000
	s_add_u32 s54, s96, 0x4000
	s_addc_u32 s55, s97, 0
	s_add_i32 s56, s42, s18
	global_load_lds_dwordx4 v200, s[96:97]
	s_mov_b32 m0, s56
	s_nop 0
	global_load_lds_dwordx4 v196, s[54:55]
	s_add_i32 m0, s56, 0x2000
	s_nop 0
	global_load_lds_dwordx4 v200, s[54:55]
	v_lshl_add_u64 v[220:221], vcc, 0, v[194:195]
	s_mov_b32 m0, s19
	s_nop 0
	global_load_lds_dwordx4 v[220:221], off
	v_lshl_add_u64 v[220:221], vcc, 0, v[198:199]
	s_mov_b32 m0, s20
	s_nop 0
	global_load_lds_dwordx4 v[220:221], off
	s_waitcnt vmcnt(8)
	s_waitcnt lgkmcnt(0)
	s_barrier
	s_waitcnt lgkmcnt(0)
	v_mfma_f32_16x16x32_bf16 v[60:63], v[64:67], v[160:163], v[60:63]
	v_mfma_f32_16x16x32_bf16 v[60:63], v[68:71], v[164:167], v[60:63]
	v_mfma_f32_16x16x32_bf16 v[56:59], v[80:83], v[160:163], v[56:59]
	v_mfma_f32_16x16x32_bf16 v[56:59], v[84:87], v[164:167], v[56:59]
	v_mfma_f32_16x16x32_bf16 v[44:47], v[64:67], v[168:171], v[44:47]
	v_mfma_f32_16x16x32_bf16 v[44:47], v[68:71], v[172:175], v[44:47]
	v_mfma_f32_16x16x32_bf16 v[40:43], v[80:83], v[168:171], v[40:43]
	v_mfma_f32_16x16x32_bf16 v[40:43], v[84:87], v[172:175], v[40:43]
	v_mfma_f32_16x16x32_bf16 v[28:31], v[64:67], v[176:179], v[28:31]
	v_mfma_f32_16x16x32_bf16 v[28:31], v[68:71], v[180:183], v[28:31]
	v_mfma_f32_16x16x32_bf16 v[24:27], v[80:83], v[176:179], v[24:27]
	v_mfma_f32_16x16x32_bf16 v[24:27], v[84:87], v[180:183], v[24:27]
	v_mfma_f32_16x16x32_bf16 v[12:15], v[64:67], v[212:215], v[12:15]
	v_mfma_f32_16x16x32_bf16 v[12:15], v[68:71], v[216:219], v[12:15]
	v_mfma_f32_16x16x32_bf16 v[8:11], v[80:83], v[212:215], v[8:11]
	v_mfma_f32_16x16x32_bf16 v[8:11], v[84:87], v[216:219], v[8:11]
	v_mfma_f32_16x16x32_bf16 v[52:55], v[144:147], v[160:163], v[52:55]
	v_mfma_f32_16x16x32_bf16 v[52:55], v[148:151], v[164:167], v[52:55]
	v_mfma_f32_16x16x32_bf16 v[48:51], v[152:155], v[160:163], v[48:51]
	v_mfma_f32_16x16x32_bf16 v[48:51], v[156:159], v[164:167], v[48:51]
	v_mfma_f32_16x16x32_bf16 v[36:39], v[144:147], v[168:171], v[36:39]
	v_mfma_f32_16x16x32_bf16 v[36:39], v[148:151], v[172:175], v[36:39]
	v_mfma_f32_16x16x32_bf16 v[32:35], v[152:155], v[168:171], v[32:35]
	v_mfma_f32_16x16x32_bf16 v[32:35], v[156:159], v[172:175], v[32:35]
	v_mfma_f32_16x16x32_bf16 v[20:23], v[144:147], v[176:179], v[20:23]
	v_mfma_f32_16x16x32_bf16 v[20:23], v[148:151], v[180:183], v[20:23]
	v_mfma_f32_16x16x32_bf16 v[16:19], v[152:155], v[176:179], v[16:19]
	v_mfma_f32_16x16x32_bf16 v[16:19], v[156:159], v[180:183], v[16:19]
	v_mfma_f32_16x16x32_bf16 v[4:7], v[144:147], v[212:215], v[4:7]
	v_mfma_f32_16x16x32_bf16 v[4:7], v[148:151], v[216:219], v[4:7]
	v_mfma_f32_16x16x32_bf16 v[0:3], v[152:155], v[212:215], v[0:3]
	v_mfma_f32_16x16x32_bf16 v[0:3], v[156:159], v[216:219], v[0:3]
	s_barrier
; #define PG8_STAGE(bufoff, gbase, voff) do { _Pragma("unroll") for (int _i = 0; _i < 2; ++_i) \
;         __builtin_amdgcn_global_load_lds((const unsigned*)((const char*)(gbase) + (voff)[_i]), (LAS unsigned*)(lds + (bufoff) + ldsw + _i * 8192), 16, 0, 0); } while (0)
; #define PG8_LDA(dst, b, h) do { _Pragma("unroll") for (int m = 0; m < 4; ++m) _Pragma("unroll") for (int k = 0; k < 2; ++k) dst[m][k] = *(const LAS bf16x8*)(lds + PG8_SA(b, h) + aoff + m * 2048 + k * 1024); } while (0)
; #define PG8_LDB(dst, b, h) do { _Pragma("unroll") for (int n = 0; n < 2; ++n) _Pragma("unroll") for (int k = 0; k < 2; ++k) dst[n][k] = *(const LAS bf16x8*)(lds + PG8_SB(b, h) + boff + n * 2048 + k * 1024); } while (0)
; #define PG8_MMA(ai, bj, At, Bt) do { __builtin_amdgcn_s_setprio(1); _Pragma("unroll") for (int m = 0; m < 4; ++m) _Pragma("unroll") for (int n = 0; n < 2; ++n) _Pragma("unroll") for (int k = 0; k < 2; ++k) \
;         acc[ai][bj][m][n] = __builtin_amdgcn_mfma_f32_16x16x32_bf16(Bt[n][k], At[m][k], acc[ai][bj][m][n], 0, 0, 0); __builtin_amdgcn_s_setprio(0); } while (0)
; #define PG8_WAIT_V(n) asm volatile("s_waitcnt vmcnt(" #n ")" ::: "memory")
; #define PG8_WAIT_L(n) asm volatile("s_waitcnt lgkmcnt(" #n ")" ::: "memory")
; #define PG8_BAR __builtin_amdgcn_s_barrier()
; #define PG8_SCHED __builtin_amdgcn_sched_barrier(0)
; template <bool ALIGN_EPI, class Epi, class Sched>
; __device__ __forceinline__ void gemm_phase(LAS unsigned char* lds, const int lda, const int ldb, const int K, const Sched& S, const Epi& E, const size_t kstepA = (size_t)(BK * 2), const size_t kstepB = (size_t)(BK * 2)) {
;     ...
;             PG8_LDB(B0, 1, 0); PG8_LDB(B1, 1, 1); PG8_SCHED; PG8_LDA(At, 1, 0); PG8_STAGE(PG8_SA(0, 1), a2 + hstepA, voffA);
;             PG8_WAIT_V(8); PG8_WAIT_L(0); PG8_BAR; PG8_MMA(0, 0, At, B0); PG8_MMA(0, 1, At, B1); PG8_BAR; PG8_SCHED;
;             PG8_LDA(At, 1, 1); PG8_STAGE(PG8_SB(1, 0), b3, voffB); PG8_STAGE(PG8_SB(1, 1), b3 + hstepB, voffB); PG8_STAGE(PG8_SA(1, 0), a3, voffA);
;             PG8_WAIT_V(8); PG8_WAIT_L(0); PG8_BAR; PG8_MMA(1, 0, At, B0); PG8_MMA(1, 1, At, B1); PG8_BAR; PG8_SCHED;
;         }
;         if constexpr (ALIGN_EPI) { if (wr == 0) PG8_BAR; }
	s_add_i32 s56, 0, 0x18000
	s_add_i32 s57, 0, 0x1c000
	v_add_u32_e32 v84, s56, v191
	v_add_u32_e32 v156, s57, v191
	ds_read_b128 v[64:67], v84
	ds_read_b128 v[68:71], v84 offset:1024
	ds_read_b128 v[80:83], v84 offset:2048
	ds_read_b128 v[84:87], v84 offset:3072
	ds_read_b128 v[144:147], v156
	ds_read_b128 v[148:151], v156 offset:1024
	ds_read_b128 v[152:155], v156 offset:2048
	ds_read_b128 v[156:159], v156 offset:3072
	s_add_u32 s54, vcc_lo, 0x4000
	s_addc_u32 s55, vcc_hi, 0
	s_mov_b32 m0, s21
	ds_read_b128 v[160:163], v233 offset:32768
	ds_read_b128 v[164:167], v233 offset:33792
	ds_read_b128 v[168:171], v233 offset:34816
	ds_read_b128 v[172:175], v233 offset:35840
	ds_read_b128 v[176:179], v233 offset:36864
	ds_read_b128 v[180:183], v233 offset:37888
	ds_read_b128 v[212:215], v233 offset:38912
	ds_read_b128 v[216:219], v233 offset:39936
	global_load_lds_dwordx4 v194, s[54:55]
	s_mov_b32 m0, s22
	s_nop 0
	global_load_lds_dwordx4 v198, s[54:55]
	s_waitcnt vmcnt(8)
	s_waitcnt lgkmcnt(0)
	s_barrier
	s_waitcnt lgkmcnt(0)
	v_mfma_f32_16x16x32_bf16 v[140:143], v[64:67], v[160:163], v[140:143]
	v_mfma_f32_16x16x32_bf16 v[140:143], v[68:71], v[164:167], v[140:143]
	v_mfma_f32_16x16x32_bf16 v[136:139], v[80:83], v[160:163], v[136:139]
	v_mfma_f32_16x16x32_bf16 v[136:139], v[84:87], v[164:167], v[136:139]
	v_mfma_f32_16x16x32_bf16 v[124:127], v[64:67], v[168:171], v[124:127]
	v_mfma_f32_16x16x32_bf16 v[124:127], v[68:71], v[172:175], v[124:127]
	v_mfma_f32_16x16x32_bf16 v[120:123], v[80:83], v[168:171], v[120:123]
	v_mfma_f32_16x16x32_bf16 v[120:123], v[84:87], v[172:175], v[120:123]
	v_mfma_f32_16x16x32_bf16 v[108:111], v[64:67], v[176:179], v[108:111]
	v_mfma_f32_16x16x32_bf16 v[108:111], v[68:71], v[180:183], v[108:111]
	v_mfma_f32_16x16x32_bf16 v[104:107], v[80:83], v[176:179], v[104:107]
	v_mfma_f32_16x16x32_bf16 v[104:107], v[84:87], v[180:183], v[104:107]
	v_mfma_f32_16x16x32_bf16 v[92:95], v[64:67], v[212:215], v[92:95]
	v_mfma_f32_16x16x32_bf16 v[92:95], v[68:71], v[216:219], v[92:95]
	v_mfma_f32_16x16x32_bf16 v[88:91], v[80:83], v[212:215], v[88:91]
	v_mfma_f32_16x16x32_bf16 v[88:91], v[84:87], v[216:219], v[88:91]
	v_mfma_f32_16x16x32_bf16 v[132:135], v[144:147], v[160:163], v[132:135]
	v_mfma_f32_16x16x32_bf16 v[132:135], v[148:151], v[164:167], v[132:135]
	v_mfma_f32_16x16x32_bf16 v[128:131], v[152:155], v[160:163], v[128:131]
	v_mfma_f32_16x16x32_bf16 v[128:131], v[156:159], v[164:167], v[128:131]
	v_mfma_f32_16x16x32_bf16 v[116:119], v[144:147], v[168:171], v[116:119]
	v_mfma_f32_16x16x32_bf16 v[116:119], v[148:151], v[172:175], v[116:119]
	v_mfma_f32_16x16x32_bf16 v[112:115], v[152:155], v[168:171], v[112:115]
	v_mfma_f32_16x16x32_bf16 v[112:115], v[156:159], v[172:175], v[112:115]
	v_mfma_f32_16x16x32_bf16 v[100:103], v[144:147], v[176:179], v[100:103]
	v_mfma_f32_16x16x32_bf16 v[100:103], v[148:151], v[180:183], v[100:103]
	v_mfma_f32_16x16x32_bf16 v[96:99], v[152:155], v[176:179], v[96:99]
	v_mfma_f32_16x16x32_bf16 v[96:99], v[156:159], v[180:183], v[96:99]
	v_mfma_f32_16x16x32_bf16 v[76:79], v[144:147], v[212:215], v[76:79]
	v_mfma_f32_16x16x32_bf16 v[76:79], v[148:151], v[216:219], v[76:79]
	v_mfma_f32_16x16x32_bf16 v[72:75], v[152:155], v[212:215], v[72:75]
	v_mfma_f32_16x16x32_bf16 v[72:75], v[156:159], v[216:219], v[72:75]
	s_barrier
	s_add_u32 s54, s96, 0x40000
	s_addc_u32 s55, s97, 0
	s_add_i32 s56, s56, s18
	s_mov_b32 m0, s56
	ds_read_b128 v[160:163], v233 offset:49152
	ds_read_b128 v[164:167], v233 offset:50176
	ds_read_b128 v[168:171], v233 offset:51200
	ds_read_b128 v[172:175], v233 offset:52224
	ds_read_b128 v[176:179], v233 offset:53248
	ds_read_b128 v[180:183], v233 offset:54272
	ds_read_b128 v[212:215], v233 offset:55296
	ds_read_b128 v[216:219], v233 offset:56320
	global_load_lds_dwordx4 v196, s[54:55]
	s_add_i32 m0, s56, 0x2000
	s_nop 0
	global_load_lds_dwordx4 v200, s[54:55]
	s_add_u32 s54, s96, 0x44000
	s_addc_u32 s55, s97, 0
	s_add_i32 s56, s57, s18
	s_mov_b32 m0, s56
	s_nop 0
	global_load_lds_dwordx4 v196, s[54:55]
	s_add_i32 m0, s56, 0x2000
	s_nop 0
	global_load_lds_dwordx4 v200, s[54:55]
	s_mov_b32 m0, s30
	s_nop 0
	global_load_lds_dwordx4 v194, s[94:95]
	s_mov_b32 m0, s31
	s_nop 0
	global_load_lds_dwordx4 v198, s[94:95]
	s_waitcnt vmcnt(8)
	s_waitcnt lgkmcnt(0)
	s_barrier
	s_waitcnt lgkmcnt(0)
	v_mfma_f32_16x16x32_bf16 v[60:63], v[64:67], v[160:163], v[60:63]
	v_mfma_f32_16x16x32_bf16 v[60:63], v[68:71], v[164:167], v[60:63]
	v_mfma_f32_16x16x32_bf16 v[56:59], v[80:83], v[160:163], v[56:59]
	v_mfma_f32_16x16x32_bf16 v[56:59], v[84:87], v[164:167], v[56:59]
	v_mfma_f32_16x16x32_bf16 v[44:47], v[64:67], v[168:171], v[44:47]
	v_mfma_f32_16x16x32_bf16 v[44:47], v[68:71], v[172:175], v[44:47]
	v_mfma_f32_16x16x32_bf16 v[40:43], v[80:83], v[168:171], v[40:43]
	v_mfma_f32_16x16x32_bf16 v[40:43], v[84:87], v[172:175], v[40:43]
	v_mfma_f32_16x16x32_bf16 v[28:31], v[64:67], v[176:179], v[28:31]
	v_mfma_f32_16x16x32_bf16 v[28:31], v[68:71], v[180:183], v[28:31]
	v_mfma_f32_16x16x32_bf16 v[24:27], v[80:83], v[176:179], v[24:27]
	v_mfma_f32_16x16x32_bf16 v[24:27], v[84:87], v[180:183], v[24:27]
	v_mfma_f32_16x16x32_bf16 v[12:15], v[64:67], v[212:215], v[12:15]
	v_mfma_f32_16x16x32_bf16 v[12:15], v[68:71], v[216:219], v[12:15]
	v_mfma_f32_16x16x32_bf16 v[8:11], v[80:83], v[212:215], v[8:11]
	v_mfma_f32_16x16x32_bf16 v[8:11], v[84:87], v[216:219], v[8:11]
	v_mfma_f32_16x16x32_bf16 v[52:55], v[144:147], v[160:163], v[52:55]
	v_mfma_f32_16x16x32_bf16 v[52:55], v[148:151], v[164:167], v[52:55]
	v_mfma_f32_16x16x32_bf16 v[48:51], v[152:155], v[160:163], v[48:51]
	v_mfma_f32_16x16x32_bf16 v[48:51], v[156:159], v[164:167], v[48:51]
	v_mfma_f32_16x16x32_bf16 v[36:39], v[144:147], v[168:171], v[36:39]
	v_mfma_f32_16x16x32_bf16 v[36:39], v[148:151], v[172:175], v[36:39]
	v_mfma_f32_16x16x32_bf16 v[32:35], v[152:155], v[168:171], v[32:35]
	v_mfma_f32_16x16x32_bf16 v[32:35], v[156:159], v[172:175], v[32:35]
	v_mfma_f32_16x16x32_bf16 v[20:23], v[144:147], v[176:179], v[20:23]
	v_mfma_f32_16x16x32_bf16 v[20:23], v[148:151], v[180:183], v[20:23]
	v_mfma_f32_16x16x32_bf16 v[16:19], v[152:155], v[176:179], v[16:19]
	v_mfma_f32_16x16x32_bf16 v[16:19], v[156:159], v[180:183], v[16:19]
	v_mfma_f32_16x16x32_bf16 v[4:7], v[144:147], v[212:215], v[4:7]
	v_mfma_f32_16x16x32_bf16 v[4:7], v[148:151], v[216:219], v[4:7]
	v_mfma_f32_16x16x32_bf16 v[0:3], v[152:155], v[212:215], v[0:3]
	v_mfma_f32_16x16x32_bf16 v[0:3], v[156:159], v[216:219], v[0:3]
	s_barrier
	s_add_i32 s51, s51, 2
	s_add_u32 s13, s13, 0x80000
	s_addc_u32 s50, s50, 0
	s_add_u32 s82, s82, 0x400000
	s_addc_u32 s83, s83, 0
	s_cmpk_gt_u32 s51, 0x55
	s_cbranch_scc0 .LBB0_218
	s_and_b64 vcc, exec, s[84:85]
	s_cbranch_vccz .LBB0_221
	s_barrier

; #define PG8_STAGE(bufoff, gbase, voff) do { _Pragma("unroll") for (int _i = 0; _i < 2; ++_i) \
;         __builtin_amdgcn_global_load_lds((const unsigned*)((const char*)(gbase) + (voff)[_i]), (LAS unsigned*)(lds + (bufoff) + ldsw + _i * 8192), 16, 0, 0); } while (0)
; #define PG8_LDA(dst, b, h) do { _Pragma("unroll") for (int m = 0; m < 4; ++m) _Pragma("unroll") for (int k = 0; k < 2; ++k) dst[m][k] = *(const LAS bf16x8*)(lds + PG8_SA(b, h) + aoff + m * 2048 + k * 1024); } while (0)
; #define PG8_LDB(dst, b, h) do { _Pragma("unroll") for (int n = 0; n < 2; ++n) _Pragma("unroll") for (int k = 0; k < 2; ++k) dst[n][k] = *(const LAS bf16x8*)(lds + PG8_SB(b, h) + boff + n * 2048 + k * 1024); } while (0)
; #define PG8_MMA(ai, bj, At, Bt) do { __builtin_amdgcn_s_setprio(1); _Pragma("unroll") for (int m = 0; m < 4; ++m) _Pragma("unroll") for (int n = 0; n < 2; ++n) _Pragma("unroll") for (int k = 0; k < 2; ++k) \
;         acc[ai][bj][m][n] = __builtin_amdgcn_mfma_f32_16x16x32_bf16(Bt[n][k], At[m][k], acc[ai][bj][m][n], 0, 0, 0); __builtin_amdgcn_s_setprio(0); } while (0)
; #define PG8_WAIT_V(n) asm volatile("s_waitcnt vmcnt(" #n ")" ::: "memory")
; #define PG8_WAIT_L(n) asm volatile("s_waitcnt lgkmcnt(" #n ")" ::: "memory")
; #define PG8_BAR __builtin_amdgcn_s_barrier()
; template <bool ALIGN_EPI, class Epi, class Sched>
; __device__ __forceinline__ void gemm_phase(LAS unsigned char* lds, const int lda, const int ldb, const int K, const Sched& S, const Epi& E, const size_t kstepA = (size_t)(BK * 2), const size_t kstepB = (size_t)(BK * 2)) {
;     ...
;             const bool last = (t == nt - 2);
;             const char* a1 = cA + (size_t)(t + 1) * kstepA;
;             const char* a2 = last ? nA : cA + (size_t)(t + 2) * kstepA; const char* b2 = last ? nB : cB + (size_t)(t + 2) * kstep;
;             const char* a3 = a2 + kstepA; const char* b3 = b2 + kstep;
;             PG8_LDB(B0, 0, 0); PG8_LDB(B1, 0, 1); PG8_SCHED; PG8_LDA(At, 0, 0); PG8_STAGE(PG8_SA(1, 1), a1 + hstepA, voffA);
;             PG8_WAIT_V(8); PG8_WAIT_L(0); PG8_BAR; PG8_MMA(0, 0, At, B0); PG8_MMA(0, 1, At, B1); PG8_BAR; PG8_SCHED;
;             PG8_LDA(At, 0, 1); PG8_STAGE(PG8_SB(0, 0), b2, voffB); PG8_STAGE(PG8_SB(0, 1), b2 + hstepB, voffB); PG8_STAGE(PG8_SA(0, 0), a2, voffA);
;             PG8_WAIT_V(8); PG8_WAIT_L(0); PG8_BAR; PG8_MMA(1, 0, At, B0); PG8_MMA(1, 1, At, B1); PG8_BAR; PG8_SCHED;
.LBB0_347:
	ds_read_b128 v[158:161], v195
	ds_read_b128 v[162:165], v195 offset:1024
	ds_read_b128 v[166:169], v195 offset:2048
	ds_read_b128 v[198:201], v195 offset:3072
	ds_read_b128 v[202:205], v196
	ds_read_b128 v[206:209], v196 offset:1024
	ds_read_b128 v[210:213], v196 offset:2048
	ds_read_b128 v[214:217], v196 offset:3072
	s_add_u32 s59, s16, 0x1fc000
	s_addc_u32 s60, s17, 0
	s_cmp_eq_u32 s58, 28
	s_cselect_b32 s94, s6, s59
	s_cselect_b32 s95, s7, s60
	s_cselect_b32 s92, s14, s55
	s_cselect_b32 s93, s15, s57
	s_add_u32 s82, s94, 0x200000
	s_addc_u32 s83, s95, 0
	s_add_i32 m0, s20, 0xc000
	ds_read_b128 v[218:221], v193
	ds_read_b128 v[222:225], v193 offset:1024
	ds_read_b128 v[226:229], v193 offset:2048
	ds_read_b128 v[230:233], v193 offset:3072
	ds_read_b128 v[234:237], v193 offset:4096
	ds_read_b128 v[238:241], v193 offset:5120
	ds_read_b128 v[242:245], v193 offset:6144
	ds_read_b128 v[246:249], v193 offset:7168
	global_load_lds_dwordx4 v150, s[16:17]
	s_add_i32 m0, s20, 0xe000
	s_nop 0
	global_load_lds_dwordx4 v152, s[16:17]
	s_waitcnt vmcnt(8)
	s_waitcnt lgkmcnt(0)
	s_barrier
	s_waitcnt lgkmcnt(0)
	v_mfma_f32_16x16x32_bf16 v[124:127], v[158:161], v[218:221], v[124:127]
	v_mfma_f32_16x16x32_bf16 v[124:127], v[162:165], v[222:225], v[124:127]
	v_mfma_f32_16x16x32_bf16 v[120:123], v[166:169], v[218:221], v[120:123]
	v_mfma_f32_16x16x32_bf16 v[120:123], v[198:201], v[222:225], v[120:123]
	v_mfma_f32_16x16x32_bf16 v[108:111], v[158:161], v[226:229], v[108:111]
	v_mfma_f32_16x16x32_bf16 v[108:111], v[162:165], v[230:233], v[108:111]
	v_mfma_f32_16x16x32_bf16 v[104:107], v[166:169], v[226:229], v[104:107]
	v_mfma_f32_16x16x32_bf16 v[104:107], v[198:201], v[230:233], v[104:107]
	v_mfma_f32_16x16x32_bf16 v[92:95], v[158:161], v[234:237], v[92:95]
	v_mfma_f32_16x16x32_bf16 v[92:95], v[162:165], v[238:241], v[92:95]
	v_mfma_f32_16x16x32_bf16 v[88:91], v[166:169], v[234:237], v[88:91]
	v_mfma_f32_16x16x32_bf16 v[88:91], v[198:201], v[238:241], v[88:91]
	v_mfma_f32_16x16x32_bf16 v[76:79], v[158:161], v[242:245], v[76:79]
	v_mfma_f32_16x16x32_bf16 v[76:79], v[162:165], v[246:249], v[76:79]
	v_mfma_f32_16x16x32_bf16 v[72:75], v[166:169], v[242:245], v[72:75]
	v_mfma_f32_16x16x32_bf16 v[72:75], v[198:201], v[246:249], v[72:75]
	v_mfma_f32_16x16x32_bf16 v[116:119], v[202:205], v[218:221], v[116:119]
	v_mfma_f32_16x16x32_bf16 v[116:119], v[206:209], v[222:225], v[116:119]
	v_mfma_f32_16x16x32_bf16 v[112:115], v[210:213], v[218:221], v[112:115]
	v_mfma_f32_16x16x32_bf16 v[112:115], v[214:217], v[222:225], v[112:115]
	v_mfma_f32_16x16x32_bf16 v[100:103], v[202:205], v[226:229], v[100:103]
	v_mfma_f32_16x16x32_bf16 v[100:103], v[206:209], v[230:233], v[100:103]
	v_mfma_f32_16x16x32_bf16 v[96:99], v[210:213], v[226:229], v[96:99]
	v_mfma_f32_16x16x32_bf16 v[96:99], v[214:217], v[230:233], v[96:99]
	v_mfma_f32_16x16x32_bf16 v[84:87], v[202:205], v[234:237], v[84:87]
	v_mfma_f32_16x16x32_bf16 v[84:87], v[206:209], v[238:241], v[84:87]
	v_mfma_f32_16x16x32_bf16 v[80:83], v[210:213], v[234:237], v[80:83]
	v_mfma_f32_16x16x32_bf16 v[80:83], v[214:217], v[238:241], v[80:83]
	v_mfma_f32_16x16x32_bf16 v[68:71], v[202:205], v[242:245], v[68:71]
	v_mfma_f32_16x16x32_bf16 v[68:71], v[206:209], v[246:249], v[68:71]
	v_mfma_f32_16x16x32_bf16 v[64:67], v[210:213], v[242:245], v[64:67]
	v_mfma_f32_16x16x32_bf16 v[64:67], v[214:217], v[246:249], v[64:67]
	s_barrier
	s_add_i32 s59, s42, s19
	s_mov_b32 m0, s59
	ds_read_b128 v[218:221], v193 offset:16384
	ds_read_b128 v[222:225], v193 offset:17408
	ds_read_b128 v[226:229], v193 offset:18432
	ds_read_b128 v[230:233], v193 offset:19456
	ds_read_b128 v[234:237], v193 offset:20480
	ds_read_b128 v[238:241], v193 offset:21504
	ds_read_b128 v[242:245], v193 offset:22528
	ds_read_b128 v[246:249], v193 offset:23552
	global_load_lds_dwordx4 v130, s[92:93]
	s_add_i32 m0, s59, 0x2000
	s_add_u32 s60, s92, 0x4000
	s_addc_u32 s61, s93, 0
	s_add_i32 s59, s43, s19
	global_load_lds_dwordx4 v134, s[92:93]
	s_mov_b32 m0, s59
	s_nop 0
	global_load_lds_dwordx4 v130, s[60:61]
	s_add_i32 m0, s59, 0x2000
	s_nop 0
	global_load_lds_dwordx4 v134, s[60:61]
	s_mov_b32 m0, s20
	s_nop 0
	global_load_lds_dwordx4 v128, s[94:95]
	s_mov_b32 m0, s21
	s_nop 0
	global_load_lds_dwordx4 v132, s[94:95]
	s_waitcnt vmcnt(8)
	s_waitcnt lgkmcnt(0)
	s_barrier
	s_waitcnt lgkmcnt(0)
	v_mfma_f32_16x16x32_bf16 v[60:63], v[158:161], v[218:221], v[60:63]
	v_mfma_f32_16x16x32_bf16 v[60:63], v[162:165], v[222:225], v[60:63]
	v_mfma_f32_16x16x32_bf16 v[56:59], v[166:169], v[218:221], v[56:59]
	v_mfma_f32_16x16x32_bf16 v[56:59], v[198:201], v[222:225], v[56:59]
	v_mfma_f32_16x16x32_bf16 v[44:47], v[158:161], v[226:229], v[44:47]
	v_mfma_f32_16x16x32_bf16 v[44:47], v[162:165], v[230:233], v[44:47]
	v_mfma_f32_16x16x32_bf16 v[40:43], v[166:169], v[226:229], v[40:43]
	v_mfma_f32_16x16x32_bf16 v[40:43], v[198:201], v[230:233], v[40:43]
	v_mfma_f32_16x16x32_bf16 v[28:31], v[158:161], v[234:237], v[28:31]
	v_mfma_f32_16x16x32_bf16 v[28:31], v[162:165], v[238:241], v[28:31]
	v_mfma_f32_16x16x32_bf16 v[24:27], v[166:169], v[234:237], v[24:27]
	v_mfma_f32_16x16x32_bf16 v[24:27], v[198:201], v[238:241], v[24:27]
	v_mfma_f32_16x16x32_bf16 v[12:15], v[158:161], v[242:245], v[12:15]
	v_mfma_f32_16x16x32_bf16 v[12:15], v[162:165], v[246:249], v[12:15]
	v_mfma_f32_16x16x32_bf16 v[8:11], v[166:169], v[242:245], v[8:11]
	v_mfma_f32_16x16x32_bf16 v[8:11], v[198:201], v[246:249], v[8:11]
	v_mfma_f32_16x16x32_bf16 v[52:55], v[202:205], v[218:221], v[52:55]
	v_mfma_f32_16x16x32_bf16 v[52:55], v[206:209], v[222:225], v[52:55]
	v_mfma_f32_16x16x32_bf16 v[48:51], v[210:213], v[218:221], v[48:51]
	v_mfma_f32_16x16x32_bf16 v[48:51], v[214:217], v[222:225], v[48:51]
	v_mfma_f32_16x16x32_bf16 v[36:39], v[202:205], v[226:229], v[36:39]
	v_mfma_f32_16x16x32_bf16 v[36:39], v[206:209], v[230:233], v[36:39]
	v_mfma_f32_16x16x32_bf16 v[32:35], v[210:213], v[226:229], v[32:35]
	v_mfma_f32_16x16x32_bf16 v[32:35], v[214:217], v[230:233], v[32:35]
	v_mfma_f32_16x16x32_bf16 v[20:23], v[202:205], v[234:237], v[20:23]
	v_mfma_f32_16x16x32_bf16 v[20:23], v[206:209], v[238:241], v[20:23]
	v_mfma_f32_16x16x32_bf16 v[16:19], v[210:213], v[234:237], v[16:19]
	v_mfma_f32_16x16x32_bf16 v[16:19], v[214:217], v[238:241], v[16:19]
	v_mfma_f32_16x16x32_bf16 v[4:7], v[202:205], v[242:245], v[4:7]
	v_mfma_f32_16x16x32_bf16 v[4:7], v[206:209], v[246:249], v[4:7]
	v_mfma_f32_16x16x32_bf16 v[0:3], v[210:213], v[242:245], v[0:3]
	v_mfma_f32_16x16x32_bf16 v[0:3], v[214:217], v[246:249], v[0:3]
	s_barrier
; #define PG8_STAGE(bufoff, gbase, voff) do { _Pragma("unroll") for (int _i = 0; _i < 2; ++_i) \
;         __builtin_amdgcn_global_load_lds((const unsigned*)((const char*)(gbase) + (voff)[_i]), (LAS unsigned*)(lds + (bufoff) + ldsw + _i * 8192), 16, 0, 0); } while (0)
; #define PG8_LDA(dst, b, h) do { _Pragma("unroll") for (int m = 0; m < 4; ++m) _Pragma("unroll") for (int k = 0; k < 2; ++k) dst[m][k] = *(const LAS bf16x8*)(lds + PG8_SA(b, h) + aoff + m * 2048 + k * 1024); } while (0)
; #define PG8_LDB(dst, b, h) do { _Pragma("unroll") for (int n = 0; n < 2; ++n) _Pragma("unroll") for (int k = 0; k < 2; ++k) dst[n][k] = *(const LAS bf16x8*)(lds + PG8_SB(b, h) + boff + n * 2048 + k * 1024); } while (0)
; #define PG8_MMA(ai, bj, At, Bt) do { __builtin_amdgcn_s_setprio(1); _Pragma("unroll") for (int m = 0; m < 4; ++m) _Pragma("unroll") for (int n = 0; n < 2; ++n) _Pragma("unroll") for (int k = 0; k < 2; ++k) \
;         acc[ai][bj][m][n] = __builtin_amdgcn_mfma_f32_16x16x32_bf16(Bt[n][k], At[m][k], acc[ai][bj][m][n], 0, 0, 0); __builtin_amdgcn_s_setprio(0); } while (0)
; #define PG8_WAIT_V(n) asm volatile("s_waitcnt vmcnt(" #n ")" ::: "memory")
; #define PG8_WAIT_L(n) asm volatile("s_waitcnt lgkmcnt(" #n ")" ::: "memory")
; #define PG8_BAR __builtin_amdgcn_s_barrier()
; #define PG8_SCHED __builtin_amdgcn_sched_barrier(0)
; template <bool ALIGN_EPI, class Epi, class Sched>
; __device__ __forceinline__ void gemm_phase(LAS unsigned char* lds, const int lda, const int ldb, const int K, const Sched& S, const Epi& E, const size_t kstepA = (size_t)(BK * 2), const size_t kstepB = (size_t)(BK * 2)) {
;     ...
;             PG8_LDB(B0, 1, 0); PG8_LDB(B1, 1, 1); PG8_SCHED; PG8_LDA(At, 1, 0); PG8_STAGE(PG8_SA(0, 1), a2 + hstepA, voffA);
;             PG8_WAIT_V(8); PG8_WAIT_L(0); PG8_BAR; PG8_MMA(0, 0, At, B0); PG8_MMA(0, 1, At, B1); PG8_BAR; PG8_SCHED;
;             PG8_LDA(At, 1, 1); PG8_STAGE(PG8_SB(1, 0), b3, voffB); PG8_STAGE(PG8_SB(1, 1), b3 + hstepB, voffB); PG8_STAGE(PG8_SA(1, 0), a3, voffA);
;             PG8_WAIT_V(8); PG8_WAIT_L(0); PG8_BAR; PG8_MMA(1, 0, At, B0); PG8_MMA(1, 1, At, B1); PG8_BAR; PG8_SCHED;
;         }
;         if constexpr (ALIGN_EPI) { if (wr == 0) PG8_BAR; }
	s_add_i32 s59, 0, 0x18000
	v_add_u32_e32 v136, s59, v141
	s_add_i32 s64, 0, 0x1c000
	ds_read_b128 v[158:161], v136
	ds_read_b128 v[162:165], v136 offset:1024
	ds_read_b128 v[166:169], v136 offset:2048
	ds_read_b128 v[198:201], v136 offset:3072
	v_add_u32_e32 v136, s64, v141
	ds_read_b128 v[202:205], v136
	ds_read_b128 v[206:209], v136 offset:1024
	ds_read_b128 v[210:213], v136 offset:2048
	ds_read_b128 v[214:217], v136 offset:3072
	s_add_u32 s60, s94, 0x4000
	s_addc_u32 s61, s95, 0
	s_mov_b32 m0, s22
	ds_read_b128 v[218:221], v193 offset:32768
	ds_read_b128 v[222:225], v193 offset:33792
	ds_read_b128 v[226:229], v193 offset:34816
	ds_read_b128 v[230:233], v193 offset:35840
	ds_read_b128 v[234:237], v193 offset:36864
	ds_read_b128 v[238:241], v193 offset:37888
	ds_read_b128 v[242:245], v193 offset:38912
	ds_read_b128 v[246:249], v193 offset:39936
	global_load_lds_dwordx4 v128, s[60:61]
	s_mov_b32 m0, s23
	s_nop 0
	global_load_lds_dwordx4 v132, s[60:61]
	s_waitcnt vmcnt(8)
	s_waitcnt lgkmcnt(0)
	s_barrier
	s_waitcnt lgkmcnt(0)
	v_mfma_f32_16x16x32_bf16 v[124:127], v[158:161], v[218:221], v[124:127]
	v_mfma_f32_16x16x32_bf16 v[124:127], v[162:165], v[222:225], v[124:127]
	v_mfma_f32_16x16x32_bf16 v[120:123], v[166:169], v[218:221], v[120:123]
	v_mfma_f32_16x16x32_bf16 v[120:123], v[198:201], v[222:225], v[120:123]
	v_mfma_f32_16x16x32_bf16 v[108:111], v[158:161], v[226:229], v[108:111]
	v_mfma_f32_16x16x32_bf16 v[108:111], v[162:165], v[230:233], v[108:111]
	v_mfma_f32_16x16x32_bf16 v[104:107], v[166:169], v[226:229], v[104:107]
	v_mfma_f32_16x16x32_bf16 v[104:107], v[198:201], v[230:233], v[104:107]
	v_mfma_f32_16x16x32_bf16 v[92:95], v[158:161], v[234:237], v[92:95]
	v_mfma_f32_16x16x32_bf16 v[92:95], v[162:165], v[238:241], v[92:95]
	v_mfma_f32_16x16x32_bf16 v[88:91], v[166:169], v[234:237], v[88:91]
	v_mfma_f32_16x16x32_bf16 v[88:91], v[198:201], v[238:241], v[88:91]
	v_mfma_f32_16x16x32_bf16 v[76:79], v[158:161], v[242:245], v[76:79]
	v_mfma_f32_16x16x32_bf16 v[76:79], v[162:165], v[246:249], v[76:79]
	v_mfma_f32_16x16x32_bf16 v[72:75], v[166:169], v[242:245], v[72:75]
	v_mfma_f32_16x16x32_bf16 v[72:75], v[198:201], v[246:249], v[72:75]
	v_mfma_f32_16x16x32_bf16 v[116:119], v[202:205], v[218:221], v[116:119]
	v_mfma_f32_16x16x32_bf16 v[116:119], v[206:209], v[222:225], v[116:119]
	v_mfma_f32_16x16x32_bf16 v[112:115], v[210:213], v[218:221], v[112:115]
	v_mfma_f32_16x16x32_bf16 v[112:115], v[214:217], v[222:225], v[112:115]
	v_mfma_f32_16x16x32_bf16 v[100:103], v[202:205], v[226:229], v[100:103]
	v_mfma_f32_16x16x32_bf16 v[100:103], v[206:209], v[230:233], v[100:103]
	v_mfma_f32_16x16x32_bf16 v[96:99], v[210:213], v[226:229], v[96:99]
	v_mfma_f32_16x16x32_bf16 v[96:99], v[214:217], v[230:233], v[96:99]
	v_mfma_f32_16x16x32_bf16 v[84:87], v[202:205], v[234:237], v[84:87]
	v_mfma_f32_16x16x32_bf16 v[84:87], v[206:209], v[238:241], v[84:87]
	v_mfma_f32_16x16x32_bf16 v[80:83], v[210:213], v[234:237], v[80:83]
	v_mfma_f32_16x16x32_bf16 v[80:83], v[214:217], v[238:241], v[80:83]
	v_mfma_f32_16x16x32_bf16 v[68:71], v[202:205], v[242:245], v[68:71]
	v_mfma_f32_16x16x32_bf16 v[68:71], v[206:209], v[246:249], v[68:71]
	v_mfma_f32_16x16x32_bf16 v[64:67], v[210:213], v[242:245], v[64:67]
	v_mfma_f32_16x16x32_bf16 v[64:67], v[214:217], v[246:249], v[64:67]
	s_barrier
	s_add_u32 s60, s92, 0x80000
	s_addc_u32 s61, s93, 0
	s_add_i32 s59, s59, s19
	s_mov_b32 m0, s59
	ds_read_b128 v[218:221], v193 offset:49152
	ds_read_b128 v[222:225], v193 offset:50176
	ds_read_b128 v[226:229], v193 offset:51200
	ds_read_b128 v[230:233], v193 offset:52224
	ds_read_b128 v[234:237], v193 offset:53248
	ds_read_b128 v[238:241], v193 offset:54272
	ds_read_b128 v[242:245], v193 offset:55296
	ds_read_b128 v[246:249], v193 offset:56320
	global_load_lds_dwordx4 v130, s[60:61]
	s_add_i32 m0, s59, 0x2000
	s_nop 0
	global_load_lds_dwordx4 v134, s[60:61]
	s_add_u32 s60, s92, 0x84000
	s_addc_u32 s61, s93, 0
	s_add_i32 s59, s64, s19
	s_mov_b32 m0, s59
	s_nop 0
	global_load_lds_dwordx4 v130, s[60:61]
	s_add_i32 m0, s59, 0x2000
	s_nop 0
	global_load_lds_dwordx4 v134, s[60:61]
	s_mov_b32 m0, s30
	s_nop 0
	global_load_lds_dwordx4 v128, s[82:83]
	s_mov_b32 m0, s31
	s_nop 0
	global_load_lds_dwordx4 v132, s[82:83]
	s_waitcnt vmcnt(8)
	s_waitcnt lgkmcnt(0)
	s_barrier
	s_waitcnt lgkmcnt(0)
	v_mfma_f32_16x16x32_bf16 v[60:63], v[158:161], v[218:221], v[60:63]
	v_mfma_f32_16x16x32_bf16 v[60:63], v[162:165], v[222:225], v[60:63]
	v_mfma_f32_16x16x32_bf16 v[56:59], v[166:169], v[218:221], v[56:59]
	v_mfma_f32_16x16x32_bf16 v[56:59], v[198:201], v[222:225], v[56:59]
	v_mfma_f32_16x16x32_bf16 v[44:47], v[158:161], v[226:229], v[44:47]
	v_mfma_f32_16x16x32_bf16 v[44:47], v[162:165], v[230:233], v[44:47]
	v_mfma_f32_16x16x32_bf16 v[40:43], v[166:169], v[226:229], v[40:43]
	v_mfma_f32_16x16x32_bf16 v[40:43], v[198:201], v[230:233], v[40:43]
	v_mfma_f32_16x16x32_bf16 v[28:31], v[158:161], v[234:237], v[28:31]
	v_mfma_f32_16x16x32_bf16 v[28:31], v[162:165], v[238:241], v[28:31]
	v_mfma_f32_16x16x32_bf16 v[24:27], v[166:169], v[234:237], v[24:27]
	v_mfma_f32_16x16x32_bf16 v[24:27], v[198:201], v[238:241], v[24:27]
	v_mfma_f32_16x16x32_bf16 v[12:15], v[158:161], v[242:245], v[12:15]
	v_mfma_f32_16x16x32_bf16 v[12:15], v[162:165], v[246:249], v[12:15]
	v_mfma_f32_16x16x32_bf16 v[8:11], v[166:169], v[242:245], v[8:11]
	v_mfma_f32_16x16x32_bf16 v[8:11], v[198:201], v[246:249], v[8:11]
	v_mfma_f32_16x16x32_bf16 v[52:55], v[202:205], v[218:221], v[52:55]
	v_mfma_f32_16x16x32_bf16 v[52:55], v[206:209], v[222:225], v[52:55]
	v_mfma_f32_16x16x32_bf16 v[48:51], v[210:213], v[218:221], v[48:51]
	v_mfma_f32_16x16x32_bf16 v[48:51], v[214:217], v[222:225], v[48:51]
	v_mfma_f32_16x16x32_bf16 v[36:39], v[202:205], v[226:229], v[36:39]
	v_mfma_f32_16x16x32_bf16 v[36:39], v[206:209], v[230:233], v[36:39]
	v_mfma_f32_16x16x32_bf16 v[32:35], v[210:213], v[226:229], v[32:35]
	v_mfma_f32_16x16x32_bf16 v[32:35], v[214:217], v[230:233], v[32:35]
	v_mfma_f32_16x16x32_bf16 v[20:23], v[202:205], v[234:237], v[20:23]
	v_mfma_f32_16x16x32_bf16 v[20:23], v[206:209], v[238:241], v[20:23]
	v_mfma_f32_16x16x32_bf16 v[16:19], v[210:213], v[234:237], v[16:19]
	v_mfma_f32_16x16x32_bf16 v[16:19], v[214:217], v[238:241], v[16:19]
	v_mfma_f32_16x16x32_bf16 v[4:7], v[202:205], v[242:245], v[4:7]
	v_mfma_f32_16x16x32_bf16 v[4:7], v[206:209], v[246:249], v[4:7]
	v_mfma_f32_16x16x32_bf16 v[0:3], v[210:213], v[242:245], v[0:3]
	v_mfma_f32_16x16x32_bf16 v[0:3], v[214:217], v[246:249], v[0:3]
	s_barrier
	s_add_i32 s58, s58, 2
	s_add_u32 s55, s55, 0x100000
	s_addc_u32 s57, s57, 0
	s_add_u32 s16, s16, 0x400000
	s_addc_u32 s17, s17, 0
	s_cmp_gt_u32 s58, 29
	s_cbranch_scc0 .LBB0_347
	s_and_b64 vcc, exec, s[68:69]
	s_cbranch_vccz .LBB0_350
	s_barrier

; #define PG8_STAGE(bufoff, gbase, voff) do { _Pragma("unroll") for (int _i = 0; _i < 2; ++_i) \
;         __builtin_amdgcn_global_load_lds((const unsigned*)((const char*)(gbase) + (voff)[_i]), (LAS unsigned*)(lds + (bufoff) + ldsw + _i * 8192), 16, 0, 0); } while (0)
; #define PG8_LDA(dst, b, h) do { _Pragma("unroll") for (int m = 0; m < 4; ++m) _Pragma("unroll") for (int k = 0; k < 2; ++k) dst[m][k] = *(const LAS bf16x8*)(lds + PG8_SA(b, h) + aoff + m * 2048 + k * 1024); } while (0)
; #define PG8_LDB(dst, b, h) do { _Pragma("unroll") for (int n = 0; n < 2; ++n) _Pragma("unroll") for (int k = 0; k < 2; ++k) dst[n][k] = *(const LAS bf16x8*)(lds + PG8_SB(b, h) + boff + n * 2048 + k * 1024); } while (0)
; #define PG8_MMA(ai, bj, At, Bt) do { __builtin_amdgcn_s_setprio(1); _Pragma("unroll") for (int m = 0; m < 4; ++m) _Pragma("unroll") for (int n = 0; n < 2; ++n) _Pragma("unroll") for (int k = 0; k < 2; ++k) \
;         acc[ai][bj][m][n] = __builtin_amdgcn_mfma_f32_16x16x32_bf16(Bt[n][k], At[m][k], acc[ai][bj][m][n], 0, 0, 0); __builtin_amdgcn_s_setprio(0); } while (0)
; #define PG8_WAIT_V(n) asm volatile("s_waitcnt vmcnt(" #n ")" ::: "memory")
; #define PG8_WAIT_L(n) asm volatile("s_waitcnt lgkmcnt(" #n ")" ::: "memory")
; #define PG8_BAR __builtin_amdgcn_s_barrier()
; template <bool ALIGN_EPI, class Epi, class Sched>
; __device__ __forceinline__ void gemm_phase(LAS unsigned char* lds, const int lda, const int ldb, const int K, const Sched& S, const Epi& E, const size_t kstepA = (size_t)(BK * 2), const size_t kstepB = (size_t)(BK * 2)) {
;     ...
;             const bool last = (t == nt - 2);
;             const char* a1 = cA + (size_t)(t + 1) * kstepA;
;             const char* a2 = last ? nA : cA + (size_t)(t + 2) * kstepA; const char* b2 = last ? nB : cB + (size_t)(t + 2) * kstep;
;             const char* a3 = a2 + kstepA; const char* b3 = b2 + kstep;
;             PG8_LDB(B0, 0, 0); PG8_LDB(B1, 0, 1); PG8_SCHED; PG8_LDA(At, 0, 0); PG8_STAGE(PG8_SA(1, 1), a1 + hstepA, voffA);
;             PG8_WAIT_V(8); PG8_WAIT_L(0); PG8_BAR; PG8_MMA(0, 0, At, B0); PG8_MMA(0, 1, At, B1); PG8_BAR; PG8_SCHED;
;             PG8_LDA(At, 0, 1); PG8_STAGE(PG8_SB(0, 0), b2, voffB); PG8_STAGE(PG8_SB(0, 1), b2 + hstepB, voffB); PG8_STAGE(PG8_SA(0, 0), a2, voffA);
;             PG8_WAIT_V(8); PG8_WAIT_L(0); PG8_BAR; PG8_MMA(1, 0, At, B0); PG8_MMA(1, 1, At, B1); PG8_BAR; PG8_SCHED;
.LBB0_726:
	ds_read_b128 v[88:91], v219
	ds_read_b128 v[92:95], v219 offset:1024
	ds_read_b128 v[112:115], v219 offset:2048
	ds_read_b128 v[116:119], v219 offset:3072
	ds_read_b128 v[144:147], v220
	ds_read_b128 v[148:151], v220 offset:1024
	ds_read_b128 v[152:155], v220 offset:2048
	ds_read_b128 v[156:159], v220 offset:3072
	s_add_u32 s14, s12, 0x1fc000
	s_addc_u32 s15, s13, 0
	s_cmp_eq_u32 s67, 28
	s_cselect_b32 s20, s0, s14
	s_cselect_b32 s21, s1, s15
	s_cselect_b32 s16, s6, s22
	s_cselect_b32 s17, s7, s23
	s_add_u32 s14, s20, 0x200000
	s_addc_u32 s15, s21, 0
	s_add_i32 m0, s19, 0xc000
	ds_read_b128 v[160:163], v221
	ds_read_b128 v[164:167], v221 offset:1024
	ds_read_b128 v[188:191], v221 offset:2048
	ds_read_b128 v[192:195], v221 offset:3072
	ds_read_b128 v[196:199], v221 offset:4096
	ds_read_b128 v[200:203], v221 offset:5120
	ds_read_b128 v[204:207], v221 offset:6144
	ds_read_b128 v[208:211], v221 offset:7168
	global_load_lds_dwordx4 v178, s[12:13]
	s_add_i32 m0, s19, 0xe000
	s_nop 0
	global_load_lds_dwordx4 v180, s[12:13]
	s_waitcnt vmcnt(8)
	s_waitcnt lgkmcnt(0)
	s_barrier
	s_waitcnt lgkmcnt(0)
	v_mfma_f32_16x16x32_bf16 v[140:143], v[88:91], v[160:163], v[140:143]
	v_mfma_f32_16x16x32_bf16 v[140:143], v[92:95], v[164:167], v[140:143]
	v_mfma_f32_16x16x32_bf16 v[136:139], v[112:115], v[160:163], v[136:139]
	v_mfma_f32_16x16x32_bf16 v[136:139], v[116:119], v[164:167], v[136:139]
	v_mfma_f32_16x16x32_bf16 v[124:127], v[88:91], v[188:191], v[124:127]
	v_mfma_f32_16x16x32_bf16 v[124:127], v[92:95], v[192:195], v[124:127]
	v_mfma_f32_16x16x32_bf16 v[120:123], v[112:115], v[188:191], v[120:123]
	v_mfma_f32_16x16x32_bf16 v[120:123], v[116:119], v[192:195], v[120:123]
	v_mfma_f32_16x16x32_bf16 v[100:103], v[88:91], v[196:199], v[100:103]
	v_mfma_f32_16x16x32_bf16 v[100:103], v[92:95], v[200:203], v[100:103]
	v_mfma_f32_16x16x32_bf16 v[96:99], v[112:115], v[196:199], v[96:99]
	v_mfma_f32_16x16x32_bf16 v[96:99], v[116:119], v[200:203], v[96:99]
	v_mfma_f32_16x16x32_bf16 v[76:79], v[88:91], v[204:207], v[76:79]
	v_mfma_f32_16x16x32_bf16 v[76:79], v[92:95], v[208:211], v[76:79]
	v_mfma_f32_16x16x32_bf16 v[72:75], v[112:115], v[204:207], v[72:75]
	v_mfma_f32_16x16x32_bf16 v[72:75], v[116:119], v[208:211], v[72:75]
	v_mfma_f32_16x16x32_bf16 v[132:135], v[144:147], v[160:163], v[132:135]
	v_mfma_f32_16x16x32_bf16 v[132:135], v[148:151], v[164:167], v[132:135]
	v_mfma_f32_16x16x32_bf16 v[128:131], v[152:155], v[160:163], v[128:131]
	v_mfma_f32_16x16x32_bf16 v[128:131], v[156:159], v[164:167], v[128:131]
	v_mfma_f32_16x16x32_bf16 v[108:111], v[144:147], v[188:191], v[108:111]
	v_mfma_f32_16x16x32_bf16 v[108:111], v[148:151], v[192:195], v[108:111]
	v_mfma_f32_16x16x32_bf16 v[104:107], v[152:155], v[188:191], v[104:107]
	v_mfma_f32_16x16x32_bf16 v[104:107], v[156:159], v[192:195], v[104:107]
	v_mfma_f32_16x16x32_bf16 v[84:87], v[144:147], v[196:199], v[84:87]
	v_mfma_f32_16x16x32_bf16 v[84:87], v[148:151], v[200:203], v[84:87]
	v_mfma_f32_16x16x32_bf16 v[80:83], v[152:155], v[196:199], v[80:83]
	v_mfma_f32_16x16x32_bf16 v[80:83], v[156:159], v[200:203], v[80:83]
	v_mfma_f32_16x16x32_bf16 v[68:71], v[144:147], v[204:207], v[68:71]
	v_mfma_f32_16x16x32_bf16 v[68:71], v[148:151], v[208:211], v[68:71]
	v_mfma_f32_16x16x32_bf16 v[64:67], v[152:155], v[204:207], v[64:67]
	v_mfma_f32_16x16x32_bf16 v[64:67], v[156:159], v[208:211], v[64:67]
	s_barrier
	s_add_i32 s69, s65, s18
	s_mov_b32 m0, s69
	ds_read_b128 v[160:163], v221 offset:16384
	ds_read_b128 v[164:167], v221 offset:17408
	ds_read_b128 v[188:191], v221 offset:18432
	ds_read_b128 v[192:195], v221 offset:19456
	ds_read_b128 v[196:199], v221 offset:20480
	ds_read_b128 v[200:203], v221 offset:21504
	ds_read_b128 v[204:207], v221 offset:22528
	ds_read_b128 v[208:211], v221 offset:23552
	global_load_lds_dwordx4 v170, s[16:17]
	s_add_i32 m0, s69, 0x2000
	s_add_u32 s78, s16, 0x4000
	s_addc_u32 s79, s17, 0
	s_add_i32 s69, s74, s18
	global_load_lds_dwordx4 v174, s[16:17]
	s_mov_b32 m0, s69
	s_nop 0
	global_load_lds_dwordx4 v170, s[78:79]
	s_add_i32 m0, s69, 0x2000
	s_nop 0
	global_load_lds_dwordx4 v174, s[78:79]
	s_mov_b32 m0, s19
	s_nop 0
	global_load_lds_dwordx4 v168, s[20:21]
	s_mov_b32 m0, s30
	s_nop 0
	global_load_lds_dwordx4 v172, s[20:21]
	s_waitcnt vmcnt(8)
	s_waitcnt lgkmcnt(0)
	s_barrier
	s_waitcnt lgkmcnt(0)
	v_mfma_f32_16x16x32_bf16 v[60:63], v[88:91], v[160:163], v[60:63]
	v_mfma_f32_16x16x32_bf16 v[60:63], v[92:95], v[164:167], v[60:63]
	v_mfma_f32_16x16x32_bf16 v[56:59], v[112:115], v[160:163], v[56:59]
	v_mfma_f32_16x16x32_bf16 v[56:59], v[116:119], v[164:167], v[56:59]
	v_mfma_f32_16x16x32_bf16 v[44:47], v[88:91], v[188:191], v[44:47]
	v_mfma_f32_16x16x32_bf16 v[44:47], v[92:95], v[192:195], v[44:47]
	v_mfma_f32_16x16x32_bf16 v[40:43], v[112:115], v[188:191], v[40:43]
	v_mfma_f32_16x16x32_bf16 v[40:43], v[116:119], v[192:195], v[40:43]
	v_mfma_f32_16x16x32_bf16 v[28:31], v[88:91], v[196:199], v[28:31]
	v_mfma_f32_16x16x32_bf16 v[28:31], v[92:95], v[200:203], v[28:31]
	v_mfma_f32_16x16x32_bf16 v[24:27], v[112:115], v[196:199], v[24:27]
	v_mfma_f32_16x16x32_bf16 v[24:27], v[116:119], v[200:203], v[24:27]
	v_mfma_f32_16x16x32_bf16 v[12:15], v[88:91], v[204:207], v[12:15]
	v_mfma_f32_16x16x32_bf16 v[12:15], v[92:95], v[208:211], v[12:15]
	v_mfma_f32_16x16x32_bf16 v[8:11], v[112:115], v[204:207], v[8:11]
	v_mfma_f32_16x16x32_bf16 v[8:11], v[116:119], v[208:211], v[8:11]
	v_mfma_f32_16x16x32_bf16 v[52:55], v[144:147], v[160:163], v[52:55]
	v_mfma_f32_16x16x32_bf16 v[52:55], v[148:151], v[164:167], v[52:55]
	v_mfma_f32_16x16x32_bf16 v[48:51], v[152:155], v[160:163], v[48:51]
	v_mfma_f32_16x16x32_bf16 v[48:51], v[156:159], v[164:167], v[48:51]
	v_mfma_f32_16x16x32_bf16 v[36:39], v[144:147], v[188:191], v[36:39]
	v_mfma_f32_16x16x32_bf16 v[36:39], v[148:151], v[192:195], v[36:39]
	v_mfma_f32_16x16x32_bf16 v[32:35], v[152:155], v[188:191], v[32:35]
	v_mfma_f32_16x16x32_bf16 v[32:35], v[156:159], v[192:195], v[32:35]
	v_mfma_f32_16x16x32_bf16 v[20:23], v[144:147], v[196:199], v[20:23]
	v_mfma_f32_16x16x32_bf16 v[20:23], v[148:151], v[200:203], v[20:23]
	v_mfma_f32_16x16x32_bf16 v[16:19], v[152:155], v[196:199], v[16:19]
	v_mfma_f32_16x16x32_bf16 v[16:19], v[156:159], v[200:203], v[16:19]
	v_mfma_f32_16x16x32_bf16 v[4:7], v[144:147], v[204:207], v[4:7]
	v_mfma_f32_16x16x32_bf16 v[4:7], v[148:151], v[208:211], v[4:7]
	v_mfma_f32_16x16x32_bf16 v[0:3], v[152:155], v[204:207], v[0:3]
	v_mfma_f32_16x16x32_bf16 v[0:3], v[156:159], v[208:211], v[0:3]
	s_barrier
; #define PG8_STAGE(bufoff, gbase, voff) do { _Pragma("unroll") for (int _i = 0; _i < 2; ++_i) \
;         __builtin_amdgcn_global_load_lds((const unsigned*)((const char*)(gbase) + (voff)[_i]), (LAS unsigned*)(lds + (bufoff) + ldsw + _i * 8192), 16, 0, 0); } while (0)
; #define PG8_LDA(dst, b, h) do { _Pragma("unroll") for (int m = 0; m < 4; ++m) _Pragma("unroll") for (int k = 0; k < 2; ++k) dst[m][k] = *(const LAS bf16x8*)(lds + PG8_SA(b, h) + aoff + m * 2048 + k * 1024); } while (0)
; #define PG8_LDB(dst, b, h) do { _Pragma("unroll") for (int n = 0; n < 2; ++n) _Pragma("unroll") for (int k = 0; k < 2; ++k) dst[n][k] = *(const LAS bf16x8*)(lds + PG8_SB(b, h) + boff + n * 2048 + k * 1024); } while (0)
; #define PG8_MMA(ai, bj, At, Bt) do { __builtin_amdgcn_s_setprio(1); _Pragma("unroll") for (int m = 0; m < 4; ++m) _Pragma("unroll") for (int n = 0; n < 2; ++n) _Pragma("unroll") for (int k = 0; k < 2; ++k) \
;         acc[ai][bj][m][n] = __builtin_amdgcn_mfma_f32_16x16x32_bf16(Bt[n][k], At[m][k], acc[ai][bj][m][n], 0, 0, 0); __builtin_amdgcn_s_setprio(0); } while (0)
; #define PG8_WAIT_V(n) asm volatile("s_waitcnt vmcnt(" #n ")" ::: "memory")
; #define PG8_WAIT_L(n) asm volatile("s_waitcnt lgkmcnt(" #n ")" ::: "memory")
; #define PG8_BAR __builtin_amdgcn_s_barrier()
; #define PG8_SCHED __builtin_amdgcn_sched_barrier(0)
; template <bool ALIGN_EPI, class Epi, class Sched>
; __device__ __forceinline__ void gemm_phase(LAS unsigned char* lds, const int lda, const int ldb, const int K, const Sched& S, const Epi& E, const size_t kstepA = (size_t)(BK * 2), const size_t kstepB = (size_t)(BK * 2)) {
;     ...
;             PG8_LDB(B0, 1, 0); PG8_LDB(B1, 1, 1); PG8_SCHED; PG8_LDA(At, 1, 0); PG8_STAGE(PG8_SA(0, 1), a2 + hstepA, voffA);
;             PG8_WAIT_V(8); PG8_WAIT_L(0); PG8_BAR; PG8_MMA(0, 0, At, B0); PG8_MMA(0, 1, At, B1); PG8_BAR; PG8_SCHED;
;             PG8_LDA(At, 1, 1); PG8_STAGE(PG8_SB(1, 0), b3, voffB); PG8_STAGE(PG8_SB(1, 1), b3 + hstepB, voffB); PG8_STAGE(PG8_SA(1, 0), a3, voffA);
;             PG8_WAIT_V(8); PG8_WAIT_L(0); PG8_BAR; PG8_MMA(1, 0, At, B0); PG8_MMA(1, 1, At, B1); PG8_BAR; PG8_SCHED;
;         }
;         if constexpr (ALIGN_EPI) { if (wr == 0) PG8_BAR; }
	s_add_i32 s69, 0, 0x18000
	s_add_i32 s77, 0, 0x1c000
	v_add_u32_e32 v116, s69, v218
	v_add_u32_e32 v156, s77, v218
	ds_read_b128 v[88:91], v116
	ds_read_b128 v[92:95], v116 offset:1024
	ds_read_b128 v[112:115], v116 offset:2048
	ds_read_b128 v[116:119], v116 offset:3072
	ds_read_b128 v[144:147], v156
	ds_read_b128 v[148:151], v156 offset:1024
	ds_read_b128 v[152:155], v156 offset:2048
	ds_read_b128 v[156:159], v156 offset:3072
	s_add_u32 s20, s20, 0x4000
	s_addc_u32 s21, s21, 0
	s_mov_b32 m0, s33
	ds_read_b128 v[160:163], v221 offset:32768
	ds_read_b128 v[164:167], v221 offset:33792
	ds_read_b128 v[188:191], v221 offset:34816
	ds_read_b128 v[192:195], v221 offset:35840
	ds_read_b128 v[196:199], v221 offset:36864
	ds_read_b128 v[200:203], v221 offset:37888
	ds_read_b128 v[204:207], v221 offset:38912
	ds_read_b128 v[208:211], v221 offset:39936
	global_load_lds_dwordx4 v168, s[20:21]
	s_mov_b32 m0, s42
	s_nop 0
	global_load_lds_dwordx4 v172, s[20:21]
	s_waitcnt vmcnt(8)
	s_waitcnt lgkmcnt(0)
	s_barrier
	s_waitcnt lgkmcnt(0)
	v_mfma_f32_16x16x32_bf16 v[140:143], v[88:91], v[160:163], v[140:143]
	v_mfma_f32_16x16x32_bf16 v[140:143], v[92:95], v[164:167], v[140:143]
	v_mfma_f32_16x16x32_bf16 v[136:139], v[112:115], v[160:163], v[136:139]
	v_mfma_f32_16x16x32_bf16 v[136:139], v[116:119], v[164:167], v[136:139]
	v_mfma_f32_16x16x32_bf16 v[124:127], v[88:91], v[188:191], v[124:127]
	v_mfma_f32_16x16x32_bf16 v[124:127], v[92:95], v[192:195], v[124:127]
	v_mfma_f32_16x16x32_bf16 v[120:123], v[112:115], v[188:191], v[120:123]
	v_mfma_f32_16x16x32_bf16 v[120:123], v[116:119], v[192:195], v[120:123]
	v_mfma_f32_16x16x32_bf16 v[100:103], v[88:91], v[196:199], v[100:103]
	v_mfma_f32_16x16x32_bf16 v[100:103], v[92:95], v[200:203], v[100:103]
	v_mfma_f32_16x16x32_bf16 v[96:99], v[112:115], v[196:199], v[96:99]
	v_mfma_f32_16x16x32_bf16 v[96:99], v[116:119], v[200:203], v[96:99]
	v_mfma_f32_16x16x32_bf16 v[76:79], v[88:91], v[204:207], v[76:79]
	v_mfma_f32_16x16x32_bf16 v[76:79], v[92:95], v[208:211], v[76:79]
	v_mfma_f32_16x16x32_bf16 v[72:75], v[112:115], v[204:207], v[72:75]
	v_mfma_f32_16x16x32_bf16 v[72:75], v[116:119], v[208:211], v[72:75]
	v_mfma_f32_16x16x32_bf16 v[132:135], v[144:147], v[160:163], v[132:135]
	v_mfma_f32_16x16x32_bf16 v[132:135], v[148:151], v[164:167], v[132:135]
	v_mfma_f32_16x16x32_bf16 v[128:131], v[152:155], v[160:163], v[128:131]
	v_mfma_f32_16x16x32_bf16 v[128:131], v[156:159], v[164:167], v[128:131]
	v_mfma_f32_16x16x32_bf16 v[108:111], v[144:147], v[188:191], v[108:111]
	v_mfma_f32_16x16x32_bf16 v[108:111], v[148:151], v[192:195], v[108:111]
	v_mfma_f32_16x16x32_bf16 v[104:107], v[152:155], v[188:191], v[104:107]
	v_mfma_f32_16x16x32_bf16 v[104:107], v[156:159], v[192:195], v[104:107]
	v_mfma_f32_16x16x32_bf16 v[84:87], v[144:147], v[196:199], v[84:87]
	v_mfma_f32_16x16x32_bf16 v[84:87], v[148:151], v[200:203], v[84:87]
	v_mfma_f32_16x16x32_bf16 v[80:83], v[152:155], v[196:199], v[80:83]
	v_mfma_f32_16x16x32_bf16 v[80:83], v[156:159], v[200:203], v[80:83]
	v_mfma_f32_16x16x32_bf16 v[68:71], v[144:147], v[204:207], v[68:71]
	v_mfma_f32_16x16x32_bf16 v[68:71], v[148:151], v[208:211], v[68:71]
	v_mfma_f32_16x16x32_bf16 v[64:67], v[152:155], v[204:207], v[64:67]
	v_mfma_f32_16x16x32_bf16 v[64:67], v[156:159], v[208:211], v[64:67]
	s_barrier
	s_add_u32 s20, s16, 0x40000
	s_addc_u32 s21, s17, 0
	s_add_i32 s69, s69, s18
	s_mov_b32 m0, s69
	ds_read_b128 v[160:163], v221 offset:49152
	ds_read_b128 v[164:167], v221 offset:50176
	ds_read_b128 v[188:191], v221 offset:51200
	ds_read_b128 v[192:195], v221 offset:52224
	ds_read_b128 v[196:199], v221 offset:53248
	ds_read_b128 v[200:203], v221 offset:54272
	ds_read_b128 v[204:207], v221 offset:55296
	ds_read_b128 v[208:211], v221 offset:56320
	global_load_lds_dwordx4 v170, s[20:21]
	s_add_i32 m0, s69, 0x2000
	s_add_u32 s16, s16, 0x44000
	global_load_lds_dwordx4 v174, s[20:21]
	s_addc_u32 s17, s17, 0
	s_add_i32 s20, s77, s18
	s_mov_b32 m0, s20
	s_nop 0
	global_load_lds_dwordx4 v170, s[16:17]
	s_add_i32 m0, s20, 0x2000
	s_nop 0
	global_load_lds_dwordx4 v174, s[16:17]
	s_mov_b32 m0, s51
	s_nop 0
	global_load_lds_dwordx4 v168, s[14:15]
	s_mov_b32 m0, s64
	s_nop 0
	global_load_lds_dwordx4 v172, s[14:15]
	s_waitcnt vmcnt(8)
	s_waitcnt lgkmcnt(0)
	s_barrier
	s_waitcnt lgkmcnt(0)
	v_mfma_f32_16x16x32_bf16 v[60:63], v[88:91], v[160:163], v[60:63]
	v_mfma_f32_16x16x32_bf16 v[60:63], v[92:95], v[164:167], v[60:63]
	v_mfma_f32_16x16x32_bf16 v[56:59], v[112:115], v[160:163], v[56:59]
	v_mfma_f32_16x16x32_bf16 v[56:59], v[116:119], v[164:167], v[56:59]
	v_mfma_f32_16x16x32_bf16 v[44:47], v[88:91], v[188:191], v[44:47]
	v_mfma_f32_16x16x32_bf16 v[44:47], v[92:95], v[192:195], v[44:47]
	v_mfma_f32_16x16x32_bf16 v[40:43], v[112:115], v[188:191], v[40:43]
	v_mfma_f32_16x16x32_bf16 v[40:43], v[116:119], v[192:195], v[40:43]
	v_mfma_f32_16x16x32_bf16 v[28:31], v[88:91], v[196:199], v[28:31]
	v_mfma_f32_16x16x32_bf16 v[28:31], v[92:95], v[200:203], v[28:31]
	v_mfma_f32_16x16x32_bf16 v[24:27], v[112:115], v[196:199], v[24:27]
	v_mfma_f32_16x16x32_bf16 v[24:27], v[116:119], v[200:203], v[24:27]
	v_mfma_f32_16x16x32_bf16 v[12:15], v[88:91], v[204:207], v[12:15]
	v_mfma_f32_16x16x32_bf16 v[12:15], v[92:95], v[208:211], v[12:15]
	v_mfma_f32_16x16x32_bf16 v[8:11], v[112:115], v[204:207], v[8:11]
	v_mfma_f32_16x16x32_bf16 v[8:11], v[116:119], v[208:211], v[8:11]
	v_mfma_f32_16x16x32_bf16 v[52:55], v[144:147], v[160:163], v[52:55]
	v_mfma_f32_16x16x32_bf16 v[52:55], v[148:151], v[164:167], v[52:55]
	v_mfma_f32_16x16x32_bf16 v[48:51], v[152:155], v[160:163], v[48:51]
	v_mfma_f32_16x16x32_bf16 v[48:51], v[156:159], v[164:167], v[48:51]
	v_mfma_f32_16x16x32_bf16 v[36:39], v[144:147], v[188:191], v[36:39]
	v_mfma_f32_16x16x32_bf16 v[36:39], v[148:151], v[192:195], v[36:39]
	v_mfma_f32_16x16x32_bf16 v[32:35], v[152:155], v[188:191], v[32:35]
	v_mfma_f32_16x16x32_bf16 v[32:35], v[156:159], v[192:195], v[32:35]
	v_mfma_f32_16x16x32_bf16 v[20:23], v[144:147], v[196:199], v[20:23]
	v_mfma_f32_16x16x32_bf16 v[20:23], v[148:151], v[200:203], v[20:23]
	v_mfma_f32_16x16x32_bf16 v[16:19], v[152:155], v[196:199], v[16:19]
	v_mfma_f32_16x16x32_bf16 v[16:19], v[156:159], v[200:203], v[16:19]
	v_mfma_f32_16x16x32_bf16 v[4:7], v[144:147], v[204:207], v[4:7]
	v_mfma_f32_16x16x32_bf16 v[4:7], v[148:151], v[208:211], v[4:7]
	v_mfma_f32_16x16x32_bf16 v[0:3], v[152:155], v[204:207], v[0:3]
	v_mfma_f32_16x16x32_bf16 v[0:3], v[156:159], v[208:211], v[0:3]
	s_barrier
	s_add_i32 s67, s67, 2
	s_add_u32 s22, s22, 0x80000
	s_addc_u32 s23, s23, 0
	s_add_u32 s12, s12, 0x400000
	s_addc_u32 s13, s13, 0
	s_cmp_gt_u32 s67, 29
	s_cbranch_scc0 .LBB0_726
	s_and_b64 vcc, exec, s[56:57]
	s_cbranch_vccz .LBB0_729
	s_barrier

; #define PG8_STAGE(bufoff, gbase, voff) do { _Pragma("unroll") for (int _i = 0; _i < 2; ++_i) \
;         __builtin_amdgcn_global_load_lds((const unsigned*)((const char*)(gbase) + (voff)[_i]), (LAS unsigned*)(lds + (bufoff) + ldsw + _i * 8192), 16, 0, 0); } while (0)
; #define PG8_LDA(dst, b, h) do { _Pragma("unroll") for (int m = 0; m < 4; ++m) _Pragma("unroll") for (int k = 0; k < 2; ++k) dst[m][k] = *(const LAS bf16x8*)(lds + PG8_SA(b, h) + aoff + m * 2048 + k * 1024); } while (0)
; #define PG8_LDB(dst, b, h) do { _Pragma("unroll") for (int n = 0; n < 2; ++n) _Pragma("unroll") for (int k = 0; k < 2; ++k) dst[n][k] = *(const LAS bf16x8*)(lds + PG8_SB(b, h) + boff + n * 2048 + k * 1024); } while (0)
; #define PG8_MMA(ai, bj, At, Bt) do { __builtin_amdgcn_s_setprio(1); _Pragma("unroll") for (int m = 0; m < 4; ++m) _Pragma("unroll") for (int n = 0; n < 2; ++n) _Pragma("unroll") for (int k = 0; k < 2; ++k) \
;         acc[ai][bj][m][n] = __builtin_amdgcn_mfma_f32_16x16x32_bf16(Bt[n][k], At[m][k], acc[ai][bj][m][n], 0, 0, 0); __builtin_amdgcn_s_setprio(0); } while (0)
; #define PG8_WAIT_V(n) asm volatile("s_waitcnt vmcnt(" #n ")" ::: "memory")
; #define PG8_WAIT_L(n) asm volatile("s_waitcnt lgkmcnt(" #n ")" ::: "memory")
; #define PG8_BAR __builtin_amdgcn_s_barrier()
; #define PG8_SCHED __builtin_amdgcn_sched_barrier(0)
; template <bool ALIGN_EPI, class Epi, class Sched>
; __device__ __forceinline__ void gemm_phase(LAS unsigned char* lds, const int lda, const int ldb, const int K, const Sched& S, const Epi& E, const size_t kstepA = (size_t)(BK * 2), const size_t kstepB = (size_t)(BK * 2)) {
;     ...
;             PG8_LDB(B0, 0, 0); PG8_LDB(B1, 0, 1); PG8_SCHED; PG8_LDA(At, 0, 0); PG8_STAGE(PG8_SA(1, 1), a1 + hstepA, voffA);
;             PG8_WAIT_V(8); PG8_WAIT_L(0); PG8_BAR; PG8_MMA(0, 0, At, B0); PG8_MMA(0, 1, At, B1); PG8_BAR; PG8_SCHED;
;             PG8_LDA(At, 0, 1); PG8_STAGE(PG8_SB(0, 0), b2, voffB); PG8_STAGE(PG8_SB(0, 1), b2 + hstepB, voffB); PG8_STAGE(PG8_SA(0, 0), a2, voffA);
;             PG8_WAIT_V(8); PG8_WAIT_L(0); PG8_BAR; PG8_MMA(1, 0, At, B0); PG8_MMA(1, 1, At, B1); PG8_BAR; PG8_SCHED;
.LBB0_952:
	ds_read_b128 v[88:91], v219
	ds_read_b128 v[92:95], v219 offset:1024
	ds_read_b128 v[112:115], v219 offset:2048
	ds_read_b128 v[116:119], v219 offset:3072
	ds_read_b128 v[144:147], v220
	ds_read_b128 v[148:151], v220 offset:1024
	ds_read_b128 v[152:155], v220 offset:2048
	ds_read_b128 v[156:159], v220 offset:3072
	s_add_u32 s14, s12, 0x1fc000
	s_addc_u32 s15, s13, 0
	s_cmp_eq_u32 s61, 12
	s_cselect_b32 s20, s0, s14
	s_cselect_b32 s21, s1, s15
	s_cselect_b32 s16, s6, s22
	s_cselect_b32 s17, s7, s23
	s_add_u32 s14, s20, 0x200000
	s_addc_u32 s15, s21, 0
	s_add_i32 m0, s19, 0xc000
	ds_read_b128 v[160:163], v221
	ds_read_b128 v[164:167], v221 offset:1024
	ds_read_b128 v[188:191], v221 offset:2048
	ds_read_b128 v[192:195], v221 offset:3072
	ds_read_b128 v[196:199], v221 offset:4096
	ds_read_b128 v[200:203], v221 offset:5120
	ds_read_b128 v[204:207], v221 offset:6144
	ds_read_b128 v[208:211], v221 offset:7168
	global_load_lds_dwordx4 v178, s[12:13]
	s_add_i32 m0, s19, 0xe000
	s_nop 0
	global_load_lds_dwordx4 v180, s[12:13]
	s_waitcnt vmcnt(8)
	s_waitcnt lgkmcnt(0)
	s_barrier
	s_waitcnt lgkmcnt(0)
	v_mfma_f32_16x16x32_bf16 v[140:143], v[88:91], v[160:163], v[140:143]
	v_mfma_f32_16x16x32_bf16 v[140:143], v[92:95], v[164:167], v[140:143]
	v_mfma_f32_16x16x32_bf16 v[136:139], v[112:115], v[160:163], v[136:139]
	v_mfma_f32_16x16x32_bf16 v[136:139], v[116:119], v[164:167], v[136:139]
	v_mfma_f32_16x16x32_bf16 v[124:127], v[88:91], v[188:191], v[124:127]
	v_mfma_f32_16x16x32_bf16 v[124:127], v[92:95], v[192:195], v[124:127]
	v_mfma_f32_16x16x32_bf16 v[120:123], v[112:115], v[188:191], v[120:123]
	v_mfma_f32_16x16x32_bf16 v[120:123], v[116:119], v[192:195], v[120:123]
	v_mfma_f32_16x16x32_bf16 v[100:103], v[88:91], v[196:199], v[100:103]
	v_mfma_f32_16x16x32_bf16 v[100:103], v[92:95], v[200:203], v[100:103]
	v_mfma_f32_16x16x32_bf16 v[96:99], v[112:115], v[196:199], v[96:99]
	v_mfma_f32_16x16x32_bf16 v[96:99], v[116:119], v[200:203], v[96:99]
	v_mfma_f32_16x16x32_bf16 v[76:79], v[88:91], v[204:207], v[76:79]
	v_mfma_f32_16x16x32_bf16 v[76:79], v[92:95], v[208:211], v[76:79]
	v_mfma_f32_16x16x32_bf16 v[72:75], v[112:115], v[204:207], v[72:75]
	v_mfma_f32_16x16x32_bf16 v[72:75], v[116:119], v[208:211], v[72:75]
	v_mfma_f32_16x16x32_bf16 v[132:135], v[144:147], v[160:163], v[132:135]
	v_mfma_f32_16x16x32_bf16 v[132:135], v[148:151], v[164:167], v[132:135]
	v_mfma_f32_16x16x32_bf16 v[128:131], v[152:155], v[160:163], v[128:131]
	v_mfma_f32_16x16x32_bf16 v[128:131], v[156:159], v[164:167], v[128:131]
	v_mfma_f32_16x16x32_bf16 v[108:111], v[144:147], v[188:191], v[108:111]
	v_mfma_f32_16x16x32_bf16 v[108:111], v[148:151], v[192:195], v[108:111]
	v_mfma_f32_16x16x32_bf16 v[104:107], v[152:155], v[188:191], v[104:107]
	v_mfma_f32_16x16x32_bf16 v[104:107], v[156:159], v[192:195], v[104:107]
	v_mfma_f32_16x16x32_bf16 v[84:87], v[144:147], v[196:199], v[84:87]
	v_mfma_f32_16x16x32_bf16 v[84:87], v[148:151], v[200:203], v[84:87]
	v_mfma_f32_16x16x32_bf16 v[80:83], v[152:155], v[196:199], v[80:83]
	v_mfma_f32_16x16x32_bf16 v[80:83], v[156:159], v[200:203], v[80:83]
	v_mfma_f32_16x16x32_bf16 v[68:71], v[144:147], v[204:207], v[68:71]
	v_mfma_f32_16x16x32_bf16 v[68:71], v[148:151], v[208:211], v[68:71]
	v_mfma_f32_16x16x32_bf16 v[64:67], v[152:155], v[204:207], v[64:67]
	v_mfma_f32_16x16x32_bf16 v[64:67], v[156:159], v[208:211], v[64:67]
	s_barrier
	s_add_i32 s63, s71, s18
	s_mov_b32 m0, s63
	ds_read_b128 v[160:163], v221 offset:16384
	ds_read_b128 v[164:167], v221 offset:17408
	ds_read_b128 v[188:191], v221 offset:18432
	ds_read_b128 v[192:195], v221 offset:19456
	ds_read_b128 v[196:199], v221 offset:20480
	ds_read_b128 v[200:203], v221 offset:21504
	ds_read_b128 v[204:207], v221 offset:22528
	ds_read_b128 v[208:211], v221 offset:23552
	global_load_lds_dwordx4 v170, s[16:17]
	s_add_i32 m0, s63, 0x2000
	s_add_u32 s76, s16, 0x4000
	s_addc_u32 s77, s17, 0
	s_add_i32 s63, s72, s18
	global_load_lds_dwordx4 v174, s[16:17]
	s_mov_b32 m0, s63
	s_nop 0
	global_load_lds_dwordx4 v170, s[76:77]
	s_add_i32 m0, s63, 0x2000
	s_nop 0
	global_load_lds_dwordx4 v174, s[76:77]
	s_mov_b32 m0, s19
	s_nop 0
	global_load_lds_dwordx4 v168, s[20:21]
	s_mov_b32 m0, s33
	s_nop 0
	global_load_lds_dwordx4 v172, s[20:21]
	s_waitcnt vmcnt(8)
	s_waitcnt lgkmcnt(0)
	s_barrier
	s_waitcnt lgkmcnt(0)
	v_mfma_f32_16x16x32_bf16 v[60:63], v[88:91], v[160:163], v[60:63]
	v_mfma_f32_16x16x32_bf16 v[60:63], v[92:95], v[164:167], v[60:63]
	v_mfma_f32_16x16x32_bf16 v[56:59], v[112:115], v[160:163], v[56:59]
	v_mfma_f32_16x16x32_bf16 v[56:59], v[116:119], v[164:167], v[56:59]
	v_mfma_f32_16x16x32_bf16 v[44:47], v[88:91], v[188:191], v[44:47]
	v_mfma_f32_16x16x32_bf16 v[44:47], v[92:95], v[192:195], v[44:47]
	v_mfma_f32_16x16x32_bf16 v[40:43], v[112:115], v[188:191], v[40:43]
	v_mfma_f32_16x16x32_bf16 v[40:43], v[116:119], v[192:195], v[40:43]
	v_mfma_f32_16x16x32_bf16 v[28:31], v[88:91], v[196:199], v[28:31]
	v_mfma_f32_16x16x32_bf16 v[28:31], v[92:95], v[200:203], v[28:31]
	v_mfma_f32_16x16x32_bf16 v[24:27], v[112:115], v[196:199], v[24:27]
	v_mfma_f32_16x16x32_bf16 v[24:27], v[116:119], v[200:203], v[24:27]
	v_mfma_f32_16x16x32_bf16 v[12:15], v[88:91], v[204:207], v[12:15]
	v_mfma_f32_16x16x32_bf16 v[12:15], v[92:95], v[208:211], v[12:15]
	v_mfma_f32_16x16x32_bf16 v[8:11], v[112:115], v[204:207], v[8:11]
	v_mfma_f32_16x16x32_bf16 v[8:11], v[116:119], v[208:211], v[8:11]
	v_mfma_f32_16x16x32_bf16 v[52:55], v[144:147], v[160:163], v[52:55]
	v_mfma_f32_16x16x32_bf16 v[52:55], v[148:151], v[164:167], v[52:55]
	v_mfma_f32_16x16x32_bf16 v[48:51], v[152:155], v[160:163], v[48:51]
	v_mfma_f32_16x16x32_bf16 v[48:51], v[156:159], v[164:167], v[48:51]
	v_mfma_f32_16x16x32_bf16 v[36:39], v[144:147], v[188:191], v[36:39]
	v_mfma_f32_16x16x32_bf16 v[36:39], v[148:151], v[192:195], v[36:39]
	v_mfma_f32_16x16x32_bf16 v[32:35], v[152:155], v[188:191], v[32:35]
	v_mfma_f32_16x16x32_bf16 v[32:35], v[156:159], v[192:195], v[32:35]
	v_mfma_f32_16x16x32_bf16 v[20:23], v[144:147], v[196:199], v[20:23]
	v_mfma_f32_16x16x32_bf16 v[20:23], v[148:151], v[200:203], v[20:23]
	v_mfma_f32_16x16x32_bf16 v[16:19], v[152:155], v[196:199], v[16:19]
	v_mfma_f32_16x16x32_bf16 v[16:19], v[156:159], v[200:203], v[16:19]
	v_mfma_f32_16x16x32_bf16 v[4:7], v[144:147], v[204:207], v[4:7]
	v_mfma_f32_16x16x32_bf16 v[4:7], v[148:151], v[208:211], v[4:7]
	v_mfma_f32_16x16x32_bf16 v[0:3], v[152:155], v[204:207], v[0:3]
	v_mfma_f32_16x16x32_bf16 v[0:3], v[156:159], v[208:211], v[0:3]
	s_barrier
; #define PG8_STAGE(bufoff, gbase, voff) do { _Pragma("unroll") for (int _i = 0; _i < 2; ++_i) \
;         __builtin_amdgcn_global_load_lds((const unsigned*)((const char*)(gbase) + (voff)[_i]), (LAS unsigned*)(lds + (bufoff) + ldsw + _i * 8192), 16, 0, 0); } while (0)
; #define PG8_LDA(dst, b, h) do { _Pragma("unroll") for (int m = 0; m < 4; ++m) _Pragma("unroll") for (int k = 0; k < 2; ++k) dst[m][k] = *(const LAS bf16x8*)(lds + PG8_SA(b, h) + aoff + m * 2048 + k * 1024); } while (0)
; #define PG8_LDB(dst, b, h) do { _Pragma("unroll") for (int n = 0; n < 2; ++n) _Pragma("unroll") for (int k = 0; k < 2; ++k) dst[n][k] = *(const LAS bf16x8*)(lds + PG8_SB(b, h) + boff + n * 2048 + k * 1024); } while (0)
; #define PG8_MMA(ai, bj, At, Bt) do { __builtin_amdgcn_s_setprio(1); _Pragma("unroll") for (int m = 0; m < 4; ++m) _Pragma("unroll") for (int n = 0; n < 2; ++n) _Pragma("unroll") for (int k = 0; k < 2; ++k) \
;         acc[ai][bj][m][n] = __builtin_amdgcn_mfma_f32_16x16x32_bf16(Bt[n][k], At[m][k], acc[ai][bj][m][n], 0, 0, 0); __builtin_amdgcn_s_setprio(0); } while (0)
; #define PG8_WAIT_V(n) asm volatile("s_waitcnt vmcnt(" #n ")" ::: "memory")
; #define PG8_WAIT_L(n) asm volatile("s_waitcnt lgkmcnt(" #n ")" ::: "memory")
; #define PG8_BAR __builtin_amdgcn_s_barrier()
; #define PG8_SCHED __builtin_amdgcn_sched_barrier(0)
; template <bool ALIGN_EPI, class Epi, class Sched>
; __device__ __forceinline__ void gemm_phase(LAS unsigned char* lds, const int lda, const int ldb, const int K, const Sched& S, const Epi& E, const size_t kstepA = (size_t)(BK * 2), const size_t kstepB = (size_t)(BK * 2)) {
;     ...
;             PG8_LDB(B0, 1, 0); PG8_LDB(B1, 1, 1); PG8_SCHED; PG8_LDA(At, 1, 0); PG8_STAGE(PG8_SA(0, 1), a2 + hstepA, voffA);
;             PG8_WAIT_V(8); PG8_WAIT_L(0); PG8_BAR; PG8_MMA(0, 0, At, B0); PG8_MMA(0, 1, At, B1); PG8_BAR; PG8_SCHED;
;             PG8_LDA(At, 1, 1); PG8_STAGE(PG8_SB(1, 0), b3, voffB); PG8_STAGE(PG8_SB(1, 1), b3 + hstepB, voffB); PG8_STAGE(PG8_SA(1, 0), a3, voffA);
;             PG8_WAIT_V(8); PG8_WAIT_L(0); PG8_BAR; PG8_MMA(1, 0, At, B0); PG8_MMA(1, 1, At, B1); PG8_BAR; PG8_SCHED;
;         }
;         if constexpr (ALIGN_EPI) { if (wr == 0) PG8_BAR; }
	s_add_i32 s63, 0, 0x18000
	s_add_i32 s75, 0, 0x1c000
	v_add_u32_e32 v116, s63, v218
	v_add_u32_e32 v156, s75, v218
	ds_read_b128 v[88:91], v116
	ds_read_b128 v[92:95], v116 offset:1024
	ds_read_b128 v[112:115], v116 offset:2048
	ds_read_b128 v[116:119], v116 offset:3072
	ds_read_b128 v[144:147], v156
	ds_read_b128 v[148:151], v156 offset:1024
	ds_read_b128 v[152:155], v156 offset:2048
	ds_read_b128 v[156:159], v156 offset:3072
	s_add_u32 s20, s20, 0x4000
	s_addc_u32 s21, s21, 0
	s_mov_b32 m0, s42
	ds_read_b128 v[160:163], v221 offset:32768
	ds_read_b128 v[164:167], v221 offset:33792
	ds_read_b128 v[188:191], v221 offset:34816
	ds_read_b128 v[192:195], v221 offset:35840
	ds_read_b128 v[196:199], v221 offset:36864
	ds_read_b128 v[200:203], v221 offset:37888
	ds_read_b128 v[204:207], v221 offset:38912
	ds_read_b128 v[208:211], v221 offset:39936
	global_load_lds_dwordx4 v168, s[20:21]
	s_mov_b32 m0, s43
	s_nop 0
	global_load_lds_dwordx4 v172, s[20:21]
	s_waitcnt vmcnt(8)
	s_waitcnt lgkmcnt(0)
	s_barrier
	s_waitcnt lgkmcnt(0)
	v_mfma_f32_16x16x32_bf16 v[140:143], v[88:91], v[160:163], v[140:143]
	v_mfma_f32_16x16x32_bf16 v[140:143], v[92:95], v[164:167], v[140:143]
	v_mfma_f32_16x16x32_bf16 v[136:139], v[112:115], v[160:163], v[136:139]
	v_mfma_f32_16x16x32_bf16 v[136:139], v[116:119], v[164:167], v[136:139]
	v_mfma_f32_16x16x32_bf16 v[124:127], v[88:91], v[188:191], v[124:127]
	v_mfma_f32_16x16x32_bf16 v[124:127], v[92:95], v[192:195], v[124:127]
	v_mfma_f32_16x16x32_bf16 v[120:123], v[112:115], v[188:191], v[120:123]
	v_mfma_f32_16x16x32_bf16 v[120:123], v[116:119], v[192:195], v[120:123]
	v_mfma_f32_16x16x32_bf16 v[100:103], v[88:91], v[196:199], v[100:103]
	v_mfma_f32_16x16x32_bf16 v[100:103], v[92:95], v[200:203], v[100:103]
	v_mfma_f32_16x16x32_bf16 v[96:99], v[112:115], v[196:199], v[96:99]
	v_mfma_f32_16x16x32_bf16 v[96:99], v[116:119], v[200:203], v[96:99]
	v_mfma_f32_16x16x32_bf16 v[76:79], v[88:91], v[204:207], v[76:79]
	v_mfma_f32_16x16x32_bf16 v[76:79], v[92:95], v[208:211], v[76:79]
	v_mfma_f32_16x16x32_bf16 v[72:75], v[112:115], v[204:207], v[72:75]
	v_mfma_f32_16x16x32_bf16 v[72:75], v[116:119], v[208:211], v[72:75]
	v_mfma_f32_16x16x32_bf16 v[132:135], v[144:147], v[160:163], v[132:135]
	v_mfma_f32_16x16x32_bf16 v[132:135], v[148:151], v[164:167], v[132:135]
	v_mfma_f32_16x16x32_bf16 v[128:131], v[152:155], v[160:163], v[128:131]
	v_mfma_f32_16x16x32_bf16 v[128:131], v[156:159], v[164:167], v[128:131]
	v_mfma_f32_16x16x32_bf16 v[108:111], v[144:147], v[188:191], v[108:111]
	v_mfma_f32_16x16x32_bf16 v[108:111], v[148:151], v[192:195], v[108:111]
	v_mfma_f32_16x16x32_bf16 v[104:107], v[152:155], v[188:191], v[104:107]
	v_mfma_f32_16x16x32_bf16 v[104:107], v[156:159], v[192:195], v[104:107]
	v_mfma_f32_16x16x32_bf16 v[84:87], v[144:147], v[196:199], v[84:87]
	v_mfma_f32_16x16x32_bf16 v[84:87], v[148:151], v[200:203], v[84:87]
	v_mfma_f32_16x16x32_bf16 v[80:83], v[152:155], v[196:199], v[80:83]
	v_mfma_f32_16x16x32_bf16 v[80:83], v[156:159], v[200:203], v[80:83]
	v_mfma_f32_16x16x32_bf16 v[68:71], v[144:147], v[204:207], v[68:71]
	v_mfma_f32_16x16x32_bf16 v[68:71], v[148:151], v[208:211], v[68:71]
	v_mfma_f32_16x16x32_bf16 v[64:67], v[152:155], v[204:207], v[64:67]
	v_mfma_f32_16x16x32_bf16 v[64:67], v[156:159], v[208:211], v[64:67]
	s_barrier
	s_add_u32 s20, s16, 0x40000
	s_addc_u32 s21, s17, 0
	s_add_i32 s63, s63, s18
	s_mov_b32 m0, s63
	ds_read_b128 v[160:163], v221 offset:49152
	ds_read_b128 v[164:167], v221 offset:50176
	ds_read_b128 v[188:191], v221 offset:51200
	ds_read_b128 v[192:195], v221 offset:52224
	ds_read_b128 v[196:199], v221 offset:53248
	ds_read_b128 v[200:203], v221 offset:54272
	ds_read_b128 v[204:207], v221 offset:55296
	ds_read_b128 v[208:211], v221 offset:56320
	global_load_lds_dwordx4 v170, s[20:21]
	s_add_i32 m0, s63, 0x2000
	s_add_u32 s16, s16, 0x44000
	global_load_lds_dwordx4 v174, s[20:21]
	s_addc_u32 s17, s17, 0
	s_add_i32 s20, s75, s18
	s_mov_b32 m0, s20
	s_nop 0
	global_load_lds_dwordx4 v170, s[16:17]
	s_add_i32 m0, s20, 0x2000
	s_nop 0
	global_load_lds_dwordx4 v174, s[16:17]
	s_mov_b32 m0, s64
	s_nop 0
	global_load_lds_dwordx4 v168, s[14:15]
	s_mov_b32 m0, s65
	s_nop 0
	global_load_lds_dwordx4 v172, s[14:15]
	s_waitcnt vmcnt(8)
	s_waitcnt lgkmcnt(0)
	s_barrier
	s_waitcnt lgkmcnt(0)
	v_mfma_f32_16x16x32_bf16 v[60:63], v[88:91], v[160:163], v[60:63]
	v_mfma_f32_16x16x32_bf16 v[60:63], v[92:95], v[164:167], v[60:63]
	v_mfma_f32_16x16x32_bf16 v[56:59], v[112:115], v[160:163], v[56:59]
	v_mfma_f32_16x16x32_bf16 v[56:59], v[116:119], v[164:167], v[56:59]
	v_mfma_f32_16x16x32_bf16 v[44:47], v[88:91], v[188:191], v[44:47]
	v_mfma_f32_16x16x32_bf16 v[44:47], v[92:95], v[192:195], v[44:47]
	v_mfma_f32_16x16x32_bf16 v[40:43], v[112:115], v[188:191], v[40:43]
	v_mfma_f32_16x16x32_bf16 v[40:43], v[116:119], v[192:195], v[40:43]
	v_mfma_f32_16x16x32_bf16 v[28:31], v[88:91], v[196:199], v[28:31]
	v_mfma_f32_16x16x32_bf16 v[28:31], v[92:95], v[200:203], v[28:31]
	v_mfma_f32_16x16x32_bf16 v[24:27], v[112:115], v[196:199], v[24:27]
	v_mfma_f32_16x16x32_bf16 v[24:27], v[116:119], v[200:203], v[24:27]
	v_mfma_f32_16x16x32_bf16 v[12:15], v[88:91], v[204:207], v[12:15]
	v_mfma_f32_16x16x32_bf16 v[12:15], v[92:95], v[208:211], v[12:15]
	v_mfma_f32_16x16x32_bf16 v[8:11], v[112:115], v[204:207], v[8:11]
	v_mfma_f32_16x16x32_bf16 v[8:11], v[116:119], v[208:211], v[8:11]
	v_mfma_f32_16x16x32_bf16 v[52:55], v[144:147], v[160:163], v[52:55]
	v_mfma_f32_16x16x32_bf16 v[52:55], v[148:151], v[164:167], v[52:55]
	v_mfma_f32_16x16x32_bf16 v[48:51], v[152:155], v[160:163], v[48:51]
	v_mfma_f32_16x16x32_bf16 v[48:51], v[156:159], v[164:167], v[48:51]
	v_mfma_f32_16x16x32_bf16 v[36:39], v[144:147], v[188:191], v[36:39]
	v_mfma_f32_16x16x32_bf16 v[36:39], v[148:151], v[192:195], v[36:39]
	v_mfma_f32_16x16x32_bf16 v[32:35], v[152:155], v[188:191], v[32:35]
	v_mfma_f32_16x16x32_bf16 v[32:35], v[156:159], v[192:195], v[32:35]
	v_mfma_f32_16x16x32_bf16 v[20:23], v[144:147], v[196:199], v[20:23]
	v_mfma_f32_16x16x32_bf16 v[20:23], v[148:151], v[200:203], v[20:23]
	v_mfma_f32_16x16x32_bf16 v[16:19], v[152:155], v[196:199], v[16:19]
	v_mfma_f32_16x16x32_bf16 v[16:19], v[156:159], v[200:203], v[16:19]
	v_mfma_f32_16x16x32_bf16 v[4:7], v[144:147], v[204:207], v[4:7]
	v_mfma_f32_16x16x32_bf16 v[4:7], v[148:151], v[208:211], v[4:7]
	v_mfma_f32_16x16x32_bf16 v[0:3], v[152:155], v[204:207], v[0:3]
	v_mfma_f32_16x16x32_bf16 v[0:3], v[156:159], v[208:211], v[0:3]
	s_barrier
	s_add_i32 s61, s61, 2
	s_add_u32 s22, s22, 0x80000
	s_addc_u32 s23, s23, 0
	s_add_u32 s12, s12, 0x400000
	s_addc_u32 s13, s13, 0
	s_cmp_gt_u32 s61, 13
	s_cbranch_scc0 .LBB0_952
	s_and_b64 vcc, exec, s[52:53]
	s_cbranch_vccz .LBB0_955
	s_barrier

; #define PG8_STAGE(bufoff, gbase, voff) do { _Pragma("unroll") for (int _i = 0; _i < 2; ++_i) \
;         __builtin_amdgcn_global_load_lds((const unsigned*)((const char*)(gbase) + (voff)[_i]), (LAS unsigned*)(lds + (bufoff) + ldsw + _i * 8192), 16, 0, 0); } while (0)
; #define PG8_LDA(dst, b, h) do { _Pragma("unroll") for (int m = 0; m < 4; ++m) _Pragma("unroll") for (int k = 0; k < 2; ++k) dst[m][k] = *(const LAS bf16x8*)(lds + PG8_SA(b, h) + aoff + m * 2048 + k * 1024); } while (0)
; #define PG8_LDB(dst, b, h) do { _Pragma("unroll") for (int n = 0; n < 2; ++n) _Pragma("unroll") for (int k = 0; k < 2; ++k) dst[n][k] = *(const LAS bf16x8*)(lds + PG8_SB(b, h) + boff + n * 2048 + k * 1024); } while (0)
; #define PG8_MMA(ai, bj, At, Bt) do { __builtin_amdgcn_s_setprio(1); _Pragma("unroll") for (int m = 0; m < 4; ++m) _Pragma("unroll") for (int n = 0; n < 2; ++n) _Pragma("unroll") for (int k = 0; k < 2; ++k) \
;         acc[ai][bj][m][n] = __builtin_amdgcn_mfma_f32_16x16x32_bf16(Bt[n][k], At[m][k], acc[ai][bj][m][n], 0, 0, 0); __builtin_amdgcn_s_setprio(0); } while (0)
; #define PG8_WAIT_V(n) asm volatile("s_waitcnt vmcnt(" #n ")" ::: "memory")
; #define PG8_WAIT_L(n) asm volatile("s_waitcnt lgkmcnt(" #n ")" ::: "memory")
; #define PG8_BAR __builtin_amdgcn_s_barrier()
; #define PG8_SCHED __builtin_amdgcn_sched_barrier(0)
; template <bool ALIGN_EPI, class Epi, class Sched>
; __device__ __forceinline__ void gemm_phase(LAS unsigned char* lds, const int lda, const int ldb, const int K, const Sched& S, const Epi& E, const size_t kstepA = (size_t)(BK * 2), const size_t kstepB = (size_t)(BK * 2)) {
;     ...
;             PG8_LDB(B0, 0, 0); PG8_LDB(B1, 0, 1); PG8_SCHED; PG8_LDA(At, 0, 0); PG8_STAGE(PG8_SA(1, 1), a1 + hstepA, voffA);
;             PG8_WAIT_V(8); PG8_WAIT_L(0); PG8_BAR; PG8_MMA(0, 0, At, B0); PG8_MMA(0, 1, At, B1); PG8_BAR; PG8_SCHED;
;             PG8_LDA(At, 0, 1); PG8_STAGE(PG8_SB(0, 0), b2, voffB); PG8_STAGE(PG8_SB(0, 1), b2 + hstepB, voffB); PG8_STAGE(PG8_SA(0, 0), a2, voffA);
;             PG8_WAIT_V(8); PG8_WAIT_L(0); PG8_BAR; PG8_MMA(1, 0, At, B0); PG8_MMA(1, 1, At, B1); PG8_BAR; PG8_SCHED;
.LBB0_1044:
	ds_read_b128 v[148:151], v168
	ds_read_b128 v[172:175], v168 offset:1024
	ds_read_b128 v[176:179], v168 offset:2048
	ds_read_b128 v[180:183], v168 offset:3072
	ds_read_b128 v[186:189], v169
	ds_read_b128 v[190:193], v169 offset:1024
	ds_read_b128 v[194:197], v169 offset:2048
	ds_read_b128 v[198:201], v169 offset:3072
	s_add_u32 s48, s46, 0x1fc000
	s_addc_u32 s49, s47, 0
	s_cmp_eq_u32 s15, 28
	s_cselect_b32 s54, s22, s48
	s_cselect_b32 s55, s23, s49
	s_cselect_b32 s52, s44, s9
	s_cselect_b32 s53, s45, s13
	s_add_u32 s48, s54, 0x200000
	s_addc_u32 s49, s55, 0
	s_add_i32 m0, s29, 0xc000
	ds_read_b128 v[202:205], v170
	ds_read_b128 v[206:209], v170 offset:1024
	ds_read_b128 v[210:213], v170 offset:2048
	ds_read_b128 v[214:217], v170 offset:3072
	ds_read_b128 v[218:221], v170 offset:4096
	ds_read_b128 v[222:225], v170 offset:5120
	ds_read_b128 v[226:229], v170 offset:6144
	ds_read_b128 v[230:233], v170 offset:7168
	global_load_lds_dwordx4 v140, s[46:47]
	s_add_i32 m0, s29, 0xe000
	s_nop 0
	global_load_lds_dwordx4 v142, s[46:47]
	s_waitcnt vmcnt(8)
	s_waitcnt lgkmcnt(0)
	s_barrier
	s_waitcnt lgkmcnt(0)
	v_mfma_f32_16x16x32_bf16 v[124:127], v[148:151], v[202:205], v[124:127]
	v_mfma_f32_16x16x32_bf16 v[124:127], v[172:175], v[206:209], v[124:127]
	v_mfma_f32_16x16x32_bf16 v[120:123], v[176:179], v[202:205], v[120:123]
	v_mfma_f32_16x16x32_bf16 v[120:123], v[180:183], v[206:209], v[120:123]
	v_mfma_f32_16x16x32_bf16 v[108:111], v[148:151], v[210:213], v[108:111]
	v_mfma_f32_16x16x32_bf16 v[108:111], v[172:175], v[214:217], v[108:111]
	v_mfma_f32_16x16x32_bf16 v[104:107], v[176:179], v[210:213], v[104:107]
	v_mfma_f32_16x16x32_bf16 v[104:107], v[180:183], v[214:217], v[104:107]
	v_mfma_f32_16x16x32_bf16 v[92:95], v[148:151], v[218:221], v[92:95]
	v_mfma_f32_16x16x32_bf16 v[92:95], v[172:175], v[222:225], v[92:95]
	v_mfma_f32_16x16x32_bf16 v[88:91], v[176:179], v[218:221], v[88:91]
	v_mfma_f32_16x16x32_bf16 v[88:91], v[180:183], v[222:225], v[88:91]
	v_mfma_f32_16x16x32_bf16 v[76:79], v[148:151], v[226:229], v[76:79]
	v_mfma_f32_16x16x32_bf16 v[76:79], v[172:175], v[230:233], v[76:79]
	v_mfma_f32_16x16x32_bf16 v[72:75], v[176:179], v[226:229], v[72:75]
	v_mfma_f32_16x16x32_bf16 v[72:75], v[180:183], v[230:233], v[72:75]
	v_mfma_f32_16x16x32_bf16 v[116:119], v[186:189], v[202:205], v[116:119]
	v_mfma_f32_16x16x32_bf16 v[116:119], v[190:193], v[206:209], v[116:119]
	v_mfma_f32_16x16x32_bf16 v[112:115], v[194:197], v[202:205], v[112:115]
	v_mfma_f32_16x16x32_bf16 v[112:115], v[198:201], v[206:209], v[112:115]
	v_mfma_f32_16x16x32_bf16 v[100:103], v[186:189], v[210:213], v[100:103]
	v_mfma_f32_16x16x32_bf16 v[100:103], v[190:193], v[214:217], v[100:103]
	v_mfma_f32_16x16x32_bf16 v[96:99], v[194:197], v[210:213], v[96:99]
	v_mfma_f32_16x16x32_bf16 v[96:99], v[198:201], v[214:217], v[96:99]
	v_mfma_f32_16x16x32_bf16 v[84:87], v[186:189], v[218:221], v[84:87]
	v_mfma_f32_16x16x32_bf16 v[84:87], v[190:193], v[222:225], v[84:87]
	v_mfma_f32_16x16x32_bf16 v[80:83], v[194:197], v[218:221], v[80:83]
	v_mfma_f32_16x16x32_bf16 v[80:83], v[198:201], v[222:225], v[80:83]
	v_mfma_f32_16x16x32_bf16 v[68:71], v[186:189], v[226:229], v[68:71]
	v_mfma_f32_16x16x32_bf16 v[68:71], v[190:193], v[230:233], v[68:71]
	v_mfma_f32_16x16x32_bf16 v[64:67], v[194:197], v[226:229], v[64:67]
	v_mfma_f32_16x16x32_bf16 v[64:67], v[198:201], v[230:233], v[64:67]
	s_barrier
	s_add_i32 s61, s57, s19
	s_mov_b32 m0, s61
	ds_read_b128 v[202:205], v170 offset:16384
	ds_read_b128 v[206:209], v170 offset:17408
	ds_read_b128 v[210:213], v170 offset:18432
	ds_read_b128 v[214:217], v170 offset:19456
	ds_read_b128 v[218:221], v170 offset:20480
	ds_read_b128 v[222:225], v170 offset:21504
	ds_read_b128 v[226:229], v170 offset:22528
	ds_read_b128 v[230:233], v170 offset:23552
	global_load_lds_dwordx4 v130, s[52:53]
	s_add_i32 m0, s61, 0x2000
	s_add_u32 s62, s52, 0x4000
	s_addc_u32 s63, s53, 0
	s_add_i32 s61, s58, s19
	global_load_lds_dwordx4 v134, s[52:53]
	s_mov_b32 m0, s61
	s_nop 0
	global_load_lds_dwordx4 v130, s[62:63]
	s_add_i32 m0, s61, 0x2000
	s_nop 0
	global_load_lds_dwordx4 v134, s[62:63]
	s_mov_b32 m0, s29
	s_nop 0
	global_load_lds_dwordx4 v128, s[54:55]
	s_mov_b32 m0, s30
	s_nop 0
	global_load_lds_dwordx4 v132, s[54:55]
	s_waitcnt vmcnt(8)
	s_waitcnt lgkmcnt(0)
	s_barrier
	s_waitcnt lgkmcnt(0)
	v_mfma_f32_16x16x32_bf16 v[60:63], v[148:151], v[202:205], v[60:63]
	v_mfma_f32_16x16x32_bf16 v[60:63], v[172:175], v[206:209], v[60:63]
	v_mfma_f32_16x16x32_bf16 v[56:59], v[176:179], v[202:205], v[56:59]
	v_mfma_f32_16x16x32_bf16 v[56:59], v[180:183], v[206:209], v[56:59]
	v_mfma_f32_16x16x32_bf16 v[44:47], v[148:151], v[210:213], v[44:47]
	v_mfma_f32_16x16x32_bf16 v[44:47], v[172:175], v[214:217], v[44:47]
	v_mfma_f32_16x16x32_bf16 v[40:43], v[176:179], v[210:213], v[40:43]
	v_mfma_f32_16x16x32_bf16 v[40:43], v[180:183], v[214:217], v[40:43]
	v_mfma_f32_16x16x32_bf16 v[28:31], v[148:151], v[218:221], v[28:31]
	v_mfma_f32_16x16x32_bf16 v[28:31], v[172:175], v[222:225], v[28:31]
	v_mfma_f32_16x16x32_bf16 v[24:27], v[176:179], v[218:221], v[24:27]
	v_mfma_f32_16x16x32_bf16 v[24:27], v[180:183], v[222:225], v[24:27]
	v_mfma_f32_16x16x32_bf16 v[12:15], v[148:151], v[226:229], v[12:15]
	v_mfma_f32_16x16x32_bf16 v[12:15], v[172:175], v[230:233], v[12:15]
	v_mfma_f32_16x16x32_bf16 v[8:11], v[176:179], v[226:229], v[8:11]
	v_mfma_f32_16x16x32_bf16 v[8:11], v[180:183], v[230:233], v[8:11]
	v_mfma_f32_16x16x32_bf16 v[52:55], v[186:189], v[202:205], v[52:55]
	v_mfma_f32_16x16x32_bf16 v[52:55], v[190:193], v[206:209], v[52:55]
	v_mfma_f32_16x16x32_bf16 v[48:51], v[194:197], v[202:205], v[48:51]
	v_mfma_f32_16x16x32_bf16 v[48:51], v[198:201], v[206:209], v[48:51]
	v_mfma_f32_16x16x32_bf16 v[36:39], v[186:189], v[210:213], v[36:39]
	v_mfma_f32_16x16x32_bf16 v[36:39], v[190:193], v[214:217], v[36:39]
	v_mfma_f32_16x16x32_bf16 v[32:35], v[194:197], v[210:213], v[32:35]
	v_mfma_f32_16x16x32_bf16 v[32:35], v[198:201], v[214:217], v[32:35]
	v_mfma_f32_16x16x32_bf16 v[20:23], v[186:189], v[218:221], v[20:23]
	v_mfma_f32_16x16x32_bf16 v[20:23], v[190:193], v[222:225], v[20:23]
	v_mfma_f32_16x16x32_bf16 v[16:19], v[194:197], v[218:221], v[16:19]
	v_mfma_f32_16x16x32_bf16 v[16:19], v[198:201], v[222:225], v[16:19]
	v_mfma_f32_16x16x32_bf16 v[4:7], v[186:189], v[226:229], v[4:7]
	v_mfma_f32_16x16x32_bf16 v[4:7], v[190:193], v[230:233], v[4:7]
	v_mfma_f32_16x16x32_bf16 v[0:3], v[194:197], v[226:229], v[0:3]
	v_mfma_f32_16x16x32_bf16 v[0:3], v[198:201], v[230:233], v[0:3]
	s_barrier
; #define PG8_STAGE(bufoff, gbase, voff) do { _Pragma("unroll") for (int _i = 0; _i < 2; ++_i) \
;         __builtin_amdgcn_global_load_lds((const unsigned*)((const char*)(gbase) + (voff)[_i]), (LAS unsigned*)(lds + (bufoff) + ldsw + _i * 8192), 16, 0, 0); } while (0)
; #define PG8_LDA(dst, b, h) do { _Pragma("unroll") for (int m = 0; m < 4; ++m) _Pragma("unroll") for (int k = 0; k < 2; ++k) dst[m][k] = *(const LAS bf16x8*)(lds + PG8_SA(b, h) + aoff + m * 2048 + k * 1024); } while (0)
; #define PG8_LDB(dst, b, h) do { _Pragma("unroll") for (int n = 0; n < 2; ++n) _Pragma("unroll") for (int k = 0; k < 2; ++k) dst[n][k] = *(const LAS bf16x8*)(lds + PG8_SB(b, h) + boff + n * 2048 + k * 1024); } while (0)
; #define PG8_MMA(ai, bj, At, Bt) do { __builtin_amdgcn_s_setprio(1); _Pragma("unroll") for (int m = 0; m < 4; ++m) _Pragma("unroll") for (int n = 0; n < 2; ++n) _Pragma("unroll") for (int k = 0; k < 2; ++k) \
;         acc[ai][bj][m][n] = __builtin_amdgcn_mfma_f32_16x16x32_bf16(Bt[n][k], At[m][k], acc[ai][bj][m][n], 0, 0, 0); __builtin_amdgcn_s_setprio(0); } while (0)
; #define PG8_WAIT_V(n) asm volatile("s_waitcnt vmcnt(" #n ")" ::: "memory")
; #define PG8_WAIT_L(n) asm volatile("s_waitcnt lgkmcnt(" #n ")" ::: "memory")
; #define PG8_BAR __builtin_amdgcn_s_barrier()
; #define PG8_SCHED __builtin_amdgcn_sched_barrier(0)
; template <bool ALIGN_EPI, class Epi, class Sched>
; __device__ __forceinline__ void gemm_phase(LAS unsigned char* lds, const int lda, const int ldb, const int K, const Sched& S, const Epi& E, const size_t kstepA = (size_t)(BK * 2), const size_t kstepB = (size_t)(BK * 2)) {
;     ...
;             PG8_LDB(B0, 1, 0); PG8_LDB(B1, 1, 1); PG8_SCHED; PG8_LDA(At, 1, 0); PG8_STAGE(PG8_SA(0, 1), a2 + hstepA, voffA);
;             PG8_WAIT_V(8); PG8_WAIT_L(0); PG8_BAR; PG8_MMA(0, 0, At, B0); PG8_MMA(0, 1, At, B1); PG8_BAR; PG8_SCHED;
;             PG8_LDA(At, 1, 1); PG8_STAGE(PG8_SB(1, 0), b3, voffB); PG8_STAGE(PG8_SB(1, 1), b3 + hstepB, voffB); PG8_STAGE(PG8_SA(1, 0), a3, voffA);
;             PG8_WAIT_V(8); PG8_WAIT_L(0); PG8_BAR; PG8_MMA(1, 0, At, B0); PG8_MMA(1, 1, At, B1); PG8_BAR; PG8_SCHED;
;         }
;         if constexpr (ALIGN_EPI) { if (wr == 0) PG8_BAR; }
	s_add_i32 s61, 0, 0x18000
	v_add_u32_e32 v136, s61, v152
	s_add_i32 s62, 0, 0x1c000
	ds_read_b128 v[148:151], v136
	ds_read_b128 v[172:175], v136 offset:1024
	ds_read_b128 v[176:179], v136 offset:2048
	ds_read_b128 v[180:183], v136 offset:3072
	v_add_u32_e32 v136, s62, v152
	ds_read_b128 v[186:189], v136
	ds_read_b128 v[190:193], v136 offset:1024
	ds_read_b128 v[194:197], v136 offset:2048
	ds_read_b128 v[198:201], v136 offset:3072
	s_add_u32 s54, s54, 0x4000
	s_addc_u32 s55, s55, 0
	s_mov_b32 m0, s31
	ds_read_b128 v[202:205], v170 offset:32768
	ds_read_b128 v[206:209], v170 offset:33792
	ds_read_b128 v[210:213], v170 offset:34816
	ds_read_b128 v[214:217], v170 offset:35840
	ds_read_b128 v[218:221], v170 offset:36864
	ds_read_b128 v[222:225], v170 offset:37888
	ds_read_b128 v[226:229], v170 offset:38912
	ds_read_b128 v[230:233], v170 offset:39936
	global_load_lds_dwordx4 v128, s[54:55]
	s_mov_b32 m0, s33
	s_nop 0
	global_load_lds_dwordx4 v132, s[54:55]
	s_waitcnt vmcnt(8)
	s_waitcnt lgkmcnt(0)
	s_barrier
	s_waitcnt lgkmcnt(0)
	v_mfma_f32_16x16x32_bf16 v[124:127], v[148:151], v[202:205], v[124:127]
	v_mfma_f32_16x16x32_bf16 v[124:127], v[172:175], v[206:209], v[124:127]
	v_mfma_f32_16x16x32_bf16 v[120:123], v[176:179], v[202:205], v[120:123]
	v_mfma_f32_16x16x32_bf16 v[120:123], v[180:183], v[206:209], v[120:123]
	v_mfma_f32_16x16x32_bf16 v[108:111], v[148:151], v[210:213], v[108:111]
	v_mfma_f32_16x16x32_bf16 v[108:111], v[172:175], v[214:217], v[108:111]
	v_mfma_f32_16x16x32_bf16 v[104:107], v[176:179], v[210:213], v[104:107]
	v_mfma_f32_16x16x32_bf16 v[104:107], v[180:183], v[214:217], v[104:107]
	v_mfma_f32_16x16x32_bf16 v[92:95], v[148:151], v[218:221], v[92:95]
	v_mfma_f32_16x16x32_bf16 v[92:95], v[172:175], v[222:225], v[92:95]
	v_mfma_f32_16x16x32_bf16 v[88:91], v[176:179], v[218:221], v[88:91]
	v_mfma_f32_16x16x32_bf16 v[88:91], v[180:183], v[222:225], v[88:91]
	v_mfma_f32_16x16x32_bf16 v[76:79], v[148:151], v[226:229], v[76:79]
	v_mfma_f32_16x16x32_bf16 v[76:79], v[172:175], v[230:233], v[76:79]
	v_mfma_f32_16x16x32_bf16 v[72:75], v[176:179], v[226:229], v[72:75]
	v_mfma_f32_16x16x32_bf16 v[72:75], v[180:183], v[230:233], v[72:75]
	v_mfma_f32_16x16x32_bf16 v[116:119], v[186:189], v[202:205], v[116:119]
	v_mfma_f32_16x16x32_bf16 v[116:119], v[190:193], v[206:209], v[116:119]
	v_mfma_f32_16x16x32_bf16 v[112:115], v[194:197], v[202:205], v[112:115]
	v_mfma_f32_16x16x32_bf16 v[112:115], v[198:201], v[206:209], v[112:115]
	v_mfma_f32_16x16x32_bf16 v[100:103], v[186:189], v[210:213], v[100:103]
	v_mfma_f32_16x16x32_bf16 v[100:103], v[190:193], v[214:217], v[100:103]
	v_mfma_f32_16x16x32_bf16 v[96:99], v[194:197], v[210:213], v[96:99]
	v_mfma_f32_16x16x32_bf16 v[96:99], v[198:201], v[214:217], v[96:99]
	v_mfma_f32_16x16x32_bf16 v[84:87], v[186:189], v[218:221], v[84:87]
	v_mfma_f32_16x16x32_bf16 v[84:87], v[190:193], v[222:225], v[84:87]
	v_mfma_f32_16x16x32_bf16 v[80:83], v[194:197], v[218:221], v[80:83]
	v_mfma_f32_16x16x32_bf16 v[80:83], v[198:201], v[222:225], v[80:83]
	v_mfma_f32_16x16x32_bf16 v[68:71], v[186:189], v[226:229], v[68:71]
	v_mfma_f32_16x16x32_bf16 v[68:71], v[190:193], v[230:233], v[68:71]
	v_mfma_f32_16x16x32_bf16 v[64:67], v[194:197], v[226:229], v[64:67]
	v_mfma_f32_16x16x32_bf16 v[64:67], v[198:201], v[230:233], v[64:67]
	s_barrier
	s_add_u32 s54, s52, 0x160000
	s_addc_u32 s55, s53, 0
	s_add_i32 s61, s61, s19
	s_mov_b32 m0, s61
	ds_read_b128 v[202:205], v170 offset:49152
	ds_read_b128 v[206:209], v170 offset:50176
	ds_read_b128 v[210:213], v170 offset:51200
	ds_read_b128 v[214:217], v170 offset:52224
	ds_read_b128 v[218:221], v170 offset:53248
	ds_read_b128 v[222:225], v170 offset:54272
	ds_read_b128 v[226:229], v170 offset:55296
	ds_read_b128 v[230:233], v170 offset:56320
	global_load_lds_dwordx4 v130, s[54:55]
	s_add_i32 m0, s61, 0x2000
	s_add_u32 s52, s52, 0x164000
	global_load_lds_dwordx4 v134, s[54:55]
	s_addc_u32 s53, s53, 0
	s_add_i32 s54, s62, s19
	s_mov_b32 m0, s54
	s_nop 0
	global_load_lds_dwordx4 v130, s[52:53]
	s_add_i32 m0, s54, 0x2000
	s_nop 0
	global_load_lds_dwordx4 v134, s[52:53]
	s_mov_b32 m0, s50
	s_nop 0
	global_load_lds_dwordx4 v128, s[48:49]
	s_mov_b32 m0, s51
	s_nop 0
	global_load_lds_dwordx4 v132, s[48:49]
	s_waitcnt vmcnt(8)
	s_waitcnt lgkmcnt(0)
	s_barrier
	s_waitcnt lgkmcnt(0)
	v_mfma_f32_16x16x32_bf16 v[60:63], v[148:151], v[202:205], v[60:63]
	v_mfma_f32_16x16x32_bf16 v[60:63], v[172:175], v[206:209], v[60:63]
	v_mfma_f32_16x16x32_bf16 v[56:59], v[176:179], v[202:205], v[56:59]
	v_mfma_f32_16x16x32_bf16 v[56:59], v[180:183], v[206:209], v[56:59]
	v_mfma_f32_16x16x32_bf16 v[44:47], v[148:151], v[210:213], v[44:47]
	v_mfma_f32_16x16x32_bf16 v[44:47], v[172:175], v[214:217], v[44:47]
	v_mfma_f32_16x16x32_bf16 v[40:43], v[176:179], v[210:213], v[40:43]
	v_mfma_f32_16x16x32_bf16 v[40:43], v[180:183], v[214:217], v[40:43]
	v_mfma_f32_16x16x32_bf16 v[28:31], v[148:151], v[218:221], v[28:31]
	v_mfma_f32_16x16x32_bf16 v[28:31], v[172:175], v[222:225], v[28:31]
	v_mfma_f32_16x16x32_bf16 v[24:27], v[176:179], v[218:221], v[24:27]
	v_mfma_f32_16x16x32_bf16 v[24:27], v[180:183], v[222:225], v[24:27]
	v_mfma_f32_16x16x32_bf16 v[12:15], v[148:151], v[226:229], v[12:15]
	v_mfma_f32_16x16x32_bf16 v[12:15], v[172:175], v[230:233], v[12:15]
	v_mfma_f32_16x16x32_bf16 v[8:11], v[176:179], v[226:229], v[8:11]
	v_mfma_f32_16x16x32_bf16 v[8:11], v[180:183], v[230:233], v[8:11]
	v_mfma_f32_16x16x32_bf16 v[52:55], v[186:189], v[202:205], v[52:55]
	v_mfma_f32_16x16x32_bf16 v[52:55], v[190:193], v[206:209], v[52:55]
	v_mfma_f32_16x16x32_bf16 v[48:51], v[194:197], v[202:205], v[48:51]
	v_mfma_f32_16x16x32_bf16 v[48:51], v[198:201], v[206:209], v[48:51]
	v_mfma_f32_16x16x32_bf16 v[36:39], v[186:189], v[210:213], v[36:39]
	v_mfma_f32_16x16x32_bf16 v[36:39], v[190:193], v[214:217], v[36:39]
	v_mfma_f32_16x16x32_bf16 v[32:35], v[194:197], v[210:213], v[32:35]
	v_mfma_f32_16x16x32_bf16 v[32:35], v[198:201], v[214:217], v[32:35]
	v_mfma_f32_16x16x32_bf16 v[20:23], v[186:189], v[218:221], v[20:23]
	v_mfma_f32_16x16x32_bf16 v[20:23], v[190:193], v[222:225], v[20:23]
	v_mfma_f32_16x16x32_bf16 v[16:19], v[194:197], v[218:221], v[16:19]
	v_mfma_f32_16x16x32_bf16 v[16:19], v[198:201], v[222:225], v[16:19]
	v_mfma_f32_16x16x32_bf16 v[4:7], v[186:189], v[226:229], v[4:7]
	v_mfma_f32_16x16x32_bf16 v[4:7], v[190:193], v[230:233], v[4:7]
	v_mfma_f32_16x16x32_bf16 v[0:3], v[194:197], v[226:229], v[0:3]
	v_mfma_f32_16x16x32_bf16 v[0:3], v[198:201], v[230:233], v[0:3]
	s_barrier
	s_add_i32 s15, s15, 2
	s_add_u32 s9, s9, 0x2c0000
	s_addc_u32 s13, s13, 0
	s_add_u32 s46, s46, 0x400000
	s_addc_u32 s47, s47, 0
	s_cmp_gt_u32 s15, 29
	s_cbranch_scc0 .LBB0_1044
	s_and_b64 vcc, exec, s[10:11]
	s_cbranch_vccz .LBB0_1047
	s_barrier

; #define PG8_STAGE(bufoff, gbase, voff) do { _Pragma("unroll") for (int _i = 0; _i < 2; ++_i) \
;         __builtin_amdgcn_global_load_lds((const unsigned*)((const char*)(gbase) + (voff)[_i]), (LAS unsigned*)(lds + (bufoff) + ldsw + _i * 8192), 16, 0, 0); } while (0)
; #define PG8_LDA(dst, b, h) do { _Pragma("unroll") for (int m = 0; m < 4; ++m) _Pragma("unroll") for (int k = 0; k < 2; ++k) dst[m][k] = *(const LAS bf16x8*)(lds + PG8_SA(b, h) + aoff + m * 2048 + k * 1024); } while (0)
; #define PG8_LDB(dst, b, h) do { _Pragma("unroll") for (int n = 0; n < 2; ++n) _Pragma("unroll") for (int k = 0; k < 2; ++k) dst[n][k] = *(const LAS bf16x8*)(lds + PG8_SB(b, h) + boff + n * 2048 + k * 1024); } while (0)
; #define PG8_MMA(ai, bj, At, Bt) do { __builtin_amdgcn_s_setprio(1); _Pragma("unroll") for (int m = 0; m < 4; ++m) _Pragma("unroll") for (int n = 0; n < 2; ++n) _Pragma("unroll") for (int k = 0; k < 2; ++k) \
;         acc[ai][bj][m][n] = __builtin_amdgcn_mfma_f32_16x16x32_bf16(Bt[n][k], At[m][k], acc[ai][bj][m][n], 0, 0, 0); __builtin_amdgcn_s_setprio(0); } while (0)
; #define PG8_WAIT_V(n) asm volatile("s_waitcnt vmcnt(" #n ")" ::: "memory")
; #define PG8_WAIT_L(n) asm volatile("s_waitcnt lgkmcnt(" #n ")" ::: "memory")
; #define PG8_BAR __builtin_amdgcn_s_barrier()
; #define PG8_SCHED __builtin_amdgcn_sched_barrier(0)
; template <bool ALIGN_EPI, class Epi, class Sched>
; __device__ __forceinline__ void gemm_phase(LAS unsigned char* lds, const int lda, const int ldb, const int K, const Sched& S, const Epi& E, const size_t kstepA = (size_t)(BK * 2), const size_t kstepB = (size_t)(BK * 2)) {
;     ...
;             PG8_LDB(B0, 0, 0); PG8_LDB(B1, 0, 1); PG8_SCHED; PG8_LDA(At, 0, 0); PG8_STAGE(PG8_SA(1, 1), a1 + hstepA, voffA);
;             PG8_WAIT_V(8); PG8_WAIT_L(0); PG8_BAR; PG8_MMA(0, 0, At, B0); PG8_MMA(0, 1, At, B1); PG8_BAR; PG8_SCHED;
;             PG8_LDA(At, 0, 1); PG8_STAGE(PG8_SB(0, 0), b2, voffB); PG8_STAGE(PG8_SB(0, 1), b2 + hstepB, voffB); PG8_STAGE(PG8_SA(0, 0), a2, voffA);
;             PG8_WAIT_V(8); PG8_WAIT_L(0); PG8_BAR; PG8_MMA(1, 0, At, B0); PG8_MMA(1, 1, At, B1); PG8_BAR; PG8_SCHED;
.LBB0_1154:
	ds_read_b128 v[80:83], v219
	ds_read_b128 v[84:87], v219 offset:1024
	ds_read_b128 v[104:107], v219 offset:2048
	ds_read_b128 v[108:111], v219 offset:3072
	ds_read_b128 v[144:147], v220
	ds_read_b128 v[148:151], v220 offset:1024
	ds_read_b128 v[152:155], v220 offset:2048
	ds_read_b128 v[156:159], v220 offset:3072
	s_add_u32 s12, s10, 0x1fc000
	s_addc_u32 s13, s11, 0
	s_cmpk_eq_i32 s67, 0x54
	s_cselect_b32 s16, s0, s12
	s_cselect_b32 s17, s1, s13
	s_cselect_b32 s14, s8, s57
	s_cselect_b32 s15, s9, s59
	s_add_u32 s12, s16, 0x200000
	s_addc_u32 s13, s17, 0
	s_add_i32 m0, s19, 0xc000
	ds_read_b128 v[160:163], v221
	ds_read_b128 v[164:167], v221 offset:1024
	ds_read_b128 v[188:191], v221 offset:2048
	ds_read_b128 v[192:195], v221 offset:3072
	ds_read_b128 v[196:199], v221 offset:4096
	ds_read_b128 v[200:203], v221 offset:5120
	ds_read_b128 v[204:207], v221 offset:6144
	ds_read_b128 v[208:211], v221 offset:7168
	global_load_lds_dwordx4 v178, s[10:11]
	s_add_i32 m0, s19, 0xe000
	s_nop 0
	global_load_lds_dwordx4 v180, s[10:11]
	s_waitcnt vmcnt(8)
	s_waitcnt lgkmcnt(0)
	s_barrier
	s_waitcnt lgkmcnt(0)
	v_mfma_f32_16x16x32_bf16 v[140:143], v[80:83], v[160:163], v[140:143]
	v_mfma_f32_16x16x32_bf16 v[140:143], v[84:87], v[164:167], v[140:143]
	v_mfma_f32_16x16x32_bf16 v[136:139], v[104:107], v[160:163], v[136:139]
	v_mfma_f32_16x16x32_bf16 v[136:139], v[108:111], v[164:167], v[136:139]
	v_mfma_f32_16x16x32_bf16 v[124:127], v[80:83], v[188:191], v[124:127]
	v_mfma_f32_16x16x32_bf16 v[124:127], v[84:87], v[192:195], v[124:127]
	v_mfma_f32_16x16x32_bf16 v[120:123], v[104:107], v[188:191], v[120:123]
	v_mfma_f32_16x16x32_bf16 v[120:123], v[108:111], v[192:195], v[120:123]
	v_mfma_f32_16x16x32_bf16 v[100:103], v[80:83], v[196:199], v[100:103]
	v_mfma_f32_16x16x32_bf16 v[100:103], v[84:87], v[200:203], v[100:103]
	v_mfma_f32_16x16x32_bf16 v[96:99], v[104:107], v[196:199], v[96:99]
	v_mfma_f32_16x16x32_bf16 v[96:99], v[108:111], v[200:203], v[96:99]
	v_mfma_f32_16x16x32_bf16 v[76:79], v[80:83], v[204:207], v[76:79]
	v_mfma_f32_16x16x32_bf16 v[76:79], v[84:87], v[208:211], v[76:79]
	v_mfma_f32_16x16x32_bf16 v[72:75], v[104:107], v[204:207], v[72:75]
	v_mfma_f32_16x16x32_bf16 v[72:75], v[108:111], v[208:211], v[72:75]
	v_mfma_f32_16x16x32_bf16 v[132:135], v[144:147], v[160:163], v[132:135]
	v_mfma_f32_16x16x32_bf16 v[132:135], v[148:151], v[164:167], v[132:135]
	v_mfma_f32_16x16x32_bf16 v[128:131], v[152:155], v[160:163], v[128:131]
	v_mfma_f32_16x16x32_bf16 v[128:131], v[156:159], v[164:167], v[128:131]
	v_mfma_f32_16x16x32_bf16 v[116:119], v[144:147], v[188:191], v[116:119]
	v_mfma_f32_16x16x32_bf16 v[116:119], v[148:151], v[192:195], v[116:119]
	v_mfma_f32_16x16x32_bf16 v[112:115], v[152:155], v[188:191], v[112:115]
	v_mfma_f32_16x16x32_bf16 v[112:115], v[156:159], v[192:195], v[112:115]
	v_mfma_f32_16x16x32_bf16 v[92:95], v[144:147], v[196:199], v[92:95]
	v_mfma_f32_16x16x32_bf16 v[92:95], v[148:151], v[200:203], v[92:95]
	v_mfma_f32_16x16x32_bf16 v[88:91], v[152:155], v[196:199], v[88:91]
	v_mfma_f32_16x16x32_bf16 v[88:91], v[156:159], v[200:203], v[88:91]
	v_mfma_f32_16x16x32_bf16 v[68:71], v[144:147], v[204:207], v[68:71]
	v_mfma_f32_16x16x32_bf16 v[68:71], v[148:151], v[208:211], v[68:71]
	v_mfma_f32_16x16x32_bf16 v[64:67], v[152:155], v[204:207], v[64:67]
	v_mfma_f32_16x16x32_bf16 v[64:67], v[156:159], v[208:211], v[64:67]
	s_barrier
	s_add_i32 s68, s51, s18
	s_mov_b32 m0, s68
	ds_read_b128 v[160:163], v221 offset:16384
	ds_read_b128 v[164:167], v221 offset:17408
	ds_read_b128 v[188:191], v221 offset:18432
	ds_read_b128 v[192:195], v221 offset:19456
	ds_read_b128 v[196:199], v221 offset:20480
	ds_read_b128 v[200:203], v221 offset:21504
	ds_read_b128 v[204:207], v221 offset:22528
	ds_read_b128 v[208:211], v221 offset:23552
	global_load_lds_dwordx4 v170, s[14:15]
	s_add_i32 m0, s68, 0x2000
	s_add_u32 s68, s14, 0x4000
	s_addc_u32 s69, s15, 0
	s_add_i32 s70, s64, s18
	global_load_lds_dwordx4 v174, s[14:15]
	s_mov_b32 m0, s70
	s_nop 0
	global_load_lds_dwordx4 v170, s[68:69]
	s_add_i32 m0, s70, 0x2000
	s_nop 0
	global_load_lds_dwordx4 v174, s[68:69]
	s_mov_b32 m0, s19
	s_nop 0
	global_load_lds_dwordx4 v168, s[16:17]
	s_mov_b32 m0, s29
	s_nop 0
	global_load_lds_dwordx4 v172, s[16:17]
	s_waitcnt vmcnt(8)
	s_waitcnt lgkmcnt(0)
	s_barrier
	s_waitcnt lgkmcnt(0)
	v_mfma_f32_16x16x32_bf16 v[60:63], v[80:83], v[160:163], v[60:63]
	v_mfma_f32_16x16x32_bf16 v[60:63], v[84:87], v[164:167], v[60:63]
	v_mfma_f32_16x16x32_bf16 v[56:59], v[104:107], v[160:163], v[56:59]
	v_mfma_f32_16x16x32_bf16 v[56:59], v[108:111], v[164:167], v[56:59]
	v_mfma_f32_16x16x32_bf16 v[44:47], v[80:83], v[188:191], v[44:47]
	v_mfma_f32_16x16x32_bf16 v[44:47], v[84:87], v[192:195], v[44:47]
	v_mfma_f32_16x16x32_bf16 v[40:43], v[104:107], v[188:191], v[40:43]
	v_mfma_f32_16x16x32_bf16 v[40:43], v[108:111], v[192:195], v[40:43]
	v_mfma_f32_16x16x32_bf16 v[28:31], v[80:83], v[196:199], v[28:31]
	v_mfma_f32_16x16x32_bf16 v[28:31], v[84:87], v[200:203], v[28:31]
	v_mfma_f32_16x16x32_bf16 v[24:27], v[104:107], v[196:199], v[24:27]
	v_mfma_f32_16x16x32_bf16 v[24:27], v[108:111], v[200:203], v[24:27]
	v_mfma_f32_16x16x32_bf16 v[12:15], v[80:83], v[204:207], v[12:15]
	v_mfma_f32_16x16x32_bf16 v[12:15], v[84:87], v[208:211], v[12:15]
	v_mfma_f32_16x16x32_bf16 v[8:11], v[104:107], v[204:207], v[8:11]
	v_mfma_f32_16x16x32_bf16 v[8:11], v[108:111], v[208:211], v[8:11]
	v_mfma_f32_16x16x32_bf16 v[52:55], v[144:147], v[160:163], v[52:55]
	v_mfma_f32_16x16x32_bf16 v[52:55], v[148:151], v[164:167], v[52:55]
	v_mfma_f32_16x16x32_bf16 v[48:51], v[152:155], v[160:163], v[48:51]
	v_mfma_f32_16x16x32_bf16 v[48:51], v[156:159], v[164:167], v[48:51]
	v_mfma_f32_16x16x32_bf16 v[36:39], v[144:147], v[188:191], v[36:39]
	v_mfma_f32_16x16x32_bf16 v[36:39], v[148:151], v[192:195], v[36:39]
	v_mfma_f32_16x16x32_bf16 v[32:35], v[152:155], v[188:191], v[32:35]
	v_mfma_f32_16x16x32_bf16 v[32:35], v[156:159], v[192:195], v[32:35]
	v_mfma_f32_16x16x32_bf16 v[20:23], v[144:147], v[196:199], v[20:23]
	v_mfma_f32_16x16x32_bf16 v[20:23], v[148:151], v[200:203], v[20:23]
	v_mfma_f32_16x16x32_bf16 v[16:19], v[152:155], v[196:199], v[16:19]
	v_mfma_f32_16x16x32_bf16 v[16:19], v[156:159], v[200:203], v[16:19]
	v_mfma_f32_16x16x32_bf16 v[4:7], v[144:147], v[204:207], v[4:7]
	v_mfma_f32_16x16x32_bf16 v[4:7], v[148:151], v[208:211], v[4:7]
	v_mfma_f32_16x16x32_bf16 v[0:3], v[152:155], v[204:207], v[0:3]
	v_mfma_f32_16x16x32_bf16 v[0:3], v[156:159], v[208:211], v[0:3]
	s_barrier
; #define PG8_STAGE(bufoff, gbase, voff) do { _Pragma("unroll") for (int _i = 0; _i < 2; ++_i) \
;         __builtin_amdgcn_global_load_lds((const unsigned*)((const char*)(gbase) + (voff)[_i]), (LAS unsigned*)(lds + (bufoff) + ldsw + _i * 8192), 16, 0, 0); } while (0)
; #define PG8_LDA(dst, b, h) do { _Pragma("unroll") for (int m = 0; m < 4; ++m) _Pragma("unroll") for (int k = 0; k < 2; ++k) dst[m][k] = *(const LAS bf16x8*)(lds + PG8_SA(b, h) + aoff + m * 2048 + k * 1024); } while (0)
; #define PG8_LDB(dst, b, h) do { _Pragma("unroll") for (int n = 0; n < 2; ++n) _Pragma("unroll") for (int k = 0; k < 2; ++k) dst[n][k] = *(const LAS bf16x8*)(lds + PG8_SB(b, h) + boff + n * 2048 + k * 1024); } while (0)
; #define PG8_MMA(ai, bj, At, Bt) do { __builtin_amdgcn_s_setprio(1); _Pragma("unroll") for (int m = 0; m < 4; ++m) _Pragma("unroll") for (int n = 0; n < 2; ++n) _Pragma("unroll") for (int k = 0; k < 2; ++k) \
;         acc[ai][bj][m][n] = __builtin_amdgcn_mfma_f32_16x16x32_bf16(Bt[n][k], At[m][k], acc[ai][bj][m][n], 0, 0, 0); __builtin_amdgcn_s_setprio(0); } while (0)
; #define PG8_WAIT_V(n) asm volatile("s_waitcnt vmcnt(" #n ")" ::: "memory")
; #define PG8_WAIT_L(n) asm volatile("s_waitcnt lgkmcnt(" #n ")" ::: "memory")
; #define PG8_BAR __builtin_amdgcn_s_barrier()
; #define PG8_SCHED __builtin_amdgcn_sched_barrier(0)
; template <bool ALIGN_EPI, class Epi, class Sched>
; __device__ __forceinline__ void gemm_phase(LAS unsigned char* lds, const int lda, const int ldb, const int K, const Sched& S, const Epi& E, const size_t kstepA = (size_t)(BK * 2), const size_t kstepB = (size_t)(BK * 2)) {
;     ...
;             PG8_LDB(B0, 1, 0); PG8_LDB(B1, 1, 1); PG8_SCHED; PG8_LDA(At, 1, 0); PG8_STAGE(PG8_SA(0, 1), a2 + hstepA, voffA);
;             PG8_WAIT_V(8); PG8_WAIT_L(0); PG8_BAR; PG8_MMA(0, 0, At, B0); PG8_MMA(0, 1, At, B1); PG8_BAR; PG8_SCHED;
;             PG8_LDA(At, 1, 1); PG8_STAGE(PG8_SB(1, 0), b3, voffB); PG8_STAGE(PG8_SB(1, 1), b3 + hstepB, voffB); PG8_STAGE(PG8_SA(1, 0), a3, voffA);
;             PG8_WAIT_V(8); PG8_WAIT_L(0); PG8_BAR; PG8_MMA(1, 0, At, B0); PG8_MMA(1, 1, At, B1); PG8_BAR; PG8_SCHED;
;         }
;         if constexpr (ALIGN_EPI) { if (wr == 0) PG8_BAR; }
	s_add_i32 s68, 0, 0x18000
	s_add_i32 s69, 0, 0x1c000
	v_add_u32_e32 v108, s68, v218
	v_add_u32_e32 v156, s69, v218
	ds_read_b128 v[80:83], v108
	ds_read_b128 v[84:87], v108 offset:1024
	ds_read_b128 v[104:107], v108 offset:2048
	ds_read_b128 v[108:111], v108 offset:3072
	ds_read_b128 v[144:147], v156
	ds_read_b128 v[148:151], v156 offset:1024
	ds_read_b128 v[152:155], v156 offset:2048
	ds_read_b128 v[156:159], v156 offset:3072
	s_add_u32 s16, s16, 0x4000
	s_addc_u32 s17, s17, 0
	s_mov_b32 m0, s30
	ds_read_b128 v[160:163], v221 offset:32768
	ds_read_b128 v[164:167], v221 offset:33792
	ds_read_b128 v[188:191], v221 offset:34816
	ds_read_b128 v[192:195], v221 offset:35840
	ds_read_b128 v[196:199], v221 offset:36864
	ds_read_b128 v[200:203], v221 offset:37888
	ds_read_b128 v[204:207], v221 offset:38912
	ds_read_b128 v[208:211], v221 offset:39936
	global_load_lds_dwordx4 v168, s[16:17]
	s_mov_b32 m0, s31
	s_nop 0
	global_load_lds_dwordx4 v172, s[16:17]
	s_waitcnt vmcnt(8)
	s_waitcnt lgkmcnt(0)
	s_barrier
	s_waitcnt lgkmcnt(0)
	v_mfma_f32_16x16x32_bf16 v[140:143], v[80:83], v[160:163], v[140:143]
	v_mfma_f32_16x16x32_bf16 v[140:143], v[84:87], v[164:167], v[140:143]
	v_mfma_f32_16x16x32_bf16 v[136:139], v[104:107], v[160:163], v[136:139]
	v_mfma_f32_16x16x32_bf16 v[136:139], v[108:111], v[164:167], v[136:139]
	v_mfma_f32_16x16x32_bf16 v[124:127], v[80:83], v[188:191], v[124:127]
	v_mfma_f32_16x16x32_bf16 v[124:127], v[84:87], v[192:195], v[124:127]
	v_mfma_f32_16x16x32_bf16 v[120:123], v[104:107], v[188:191], v[120:123]
	v_mfma_f32_16x16x32_bf16 v[120:123], v[108:111], v[192:195], v[120:123]
	v_mfma_f32_16x16x32_bf16 v[100:103], v[80:83], v[196:199], v[100:103]
	v_mfma_f32_16x16x32_bf16 v[100:103], v[84:87], v[200:203], v[100:103]
	v_mfma_f32_16x16x32_bf16 v[96:99], v[104:107], v[196:199], v[96:99]
	v_mfma_f32_16x16x32_bf16 v[96:99], v[108:111], v[200:203], v[96:99]
	v_mfma_f32_16x16x32_bf16 v[76:79], v[80:83], v[204:207], v[76:79]
	v_mfma_f32_16x16x32_bf16 v[76:79], v[84:87], v[208:211], v[76:79]
	v_mfma_f32_16x16x32_bf16 v[72:75], v[104:107], v[204:207], v[72:75]
	v_mfma_f32_16x16x32_bf16 v[72:75], v[108:111], v[208:211], v[72:75]
	v_mfma_f32_16x16x32_bf16 v[132:135], v[144:147], v[160:163], v[132:135]
	v_mfma_f32_16x16x32_bf16 v[132:135], v[148:151], v[164:167], v[132:135]
	v_mfma_f32_16x16x32_bf16 v[128:131], v[152:155], v[160:163], v[128:131]
	v_mfma_f32_16x16x32_bf16 v[128:131], v[156:159], v[164:167], v[128:131]
	v_mfma_f32_16x16x32_bf16 v[116:119], v[144:147], v[188:191], v[116:119]
	v_mfma_f32_16x16x32_bf16 v[116:119], v[148:151], v[192:195], v[116:119]
	v_mfma_f32_16x16x32_bf16 v[112:115], v[152:155], v[188:191], v[112:115]
	v_mfma_f32_16x16x32_bf16 v[112:115], v[156:159], v[192:195], v[112:115]
	v_mfma_f32_16x16x32_bf16 v[92:95], v[144:147], v[196:199], v[92:95]
	v_mfma_f32_16x16x32_bf16 v[92:95], v[148:151], v[200:203], v[92:95]
	v_mfma_f32_16x16x32_bf16 v[88:91], v[152:155], v[196:199], v[88:91]
	v_mfma_f32_16x16x32_bf16 v[88:91], v[156:159], v[200:203], v[88:91]
	v_mfma_f32_16x16x32_bf16 v[68:71], v[144:147], v[204:207], v[68:71]
	v_mfma_f32_16x16x32_bf16 v[68:71], v[148:151], v[208:211], v[68:71]
	v_mfma_f32_16x16x32_bf16 v[64:67], v[152:155], v[204:207], v[64:67]
	v_mfma_f32_16x16x32_bf16 v[64:67], v[156:159], v[208:211], v[64:67]
	s_barrier
	s_add_u32 s16, s14, 0x40000
	s_addc_u32 s17, s15, 0
	s_add_i32 s68, s68, s18
	s_mov_b32 m0, s68
	ds_read_b128 v[160:163], v221 offset:49152
	ds_read_b128 v[164:167], v221 offset:50176
	ds_read_b128 v[188:191], v221 offset:51200
	ds_read_b128 v[192:195], v221 offset:52224
	ds_read_b128 v[196:199], v221 offset:53248
	ds_read_b128 v[200:203], v221 offset:54272
	ds_read_b128 v[204:207], v221 offset:55296
	ds_read_b128 v[208:211], v221 offset:56320
	global_load_lds_dwordx4 v170, s[16:17]
	s_add_i32 m0, s68, 0x2000
	s_add_u32 s14, s14, 0x44000
	global_load_lds_dwordx4 v174, s[16:17]
	s_addc_u32 s15, s15, 0
	s_add_i32 s16, s69, s18
	s_mov_b32 m0, s16
	s_nop 0
	global_load_lds_dwordx4 v170, s[14:15]
	s_add_i32 m0, s16, 0x2000
	s_nop 0
	global_load_lds_dwordx4 v174, s[14:15]
	s_mov_b32 m0, s43
	s_nop 0
	global_load_lds_dwordx4 v168, s[12:13]
	s_mov_b32 m0, s50
	s_nop 0
	global_load_lds_dwordx4 v172, s[12:13]
	s_waitcnt vmcnt(8)
	s_waitcnt lgkmcnt(0)
	s_barrier
	s_waitcnt lgkmcnt(0)
	v_mfma_f32_16x16x32_bf16 v[60:63], v[80:83], v[160:163], v[60:63]
	v_mfma_f32_16x16x32_bf16 v[60:63], v[84:87], v[164:167], v[60:63]
	v_mfma_f32_16x16x32_bf16 v[56:59], v[104:107], v[160:163], v[56:59]
	v_mfma_f32_16x16x32_bf16 v[56:59], v[108:111], v[164:167], v[56:59]
	v_mfma_f32_16x16x32_bf16 v[44:47], v[80:83], v[188:191], v[44:47]
	v_mfma_f32_16x16x32_bf16 v[44:47], v[84:87], v[192:195], v[44:47]
	v_mfma_f32_16x16x32_bf16 v[40:43], v[104:107], v[188:191], v[40:43]
	v_mfma_f32_16x16x32_bf16 v[40:43], v[108:111], v[192:195], v[40:43]
	v_mfma_f32_16x16x32_bf16 v[28:31], v[80:83], v[196:199], v[28:31]
	v_mfma_f32_16x16x32_bf16 v[28:31], v[84:87], v[200:203], v[28:31]
	v_mfma_f32_16x16x32_bf16 v[24:27], v[104:107], v[196:199], v[24:27]
	v_mfma_f32_16x16x32_bf16 v[24:27], v[108:111], v[200:203], v[24:27]
	v_mfma_f32_16x16x32_bf16 v[12:15], v[80:83], v[204:207], v[12:15]
	v_mfma_f32_16x16x32_bf16 v[12:15], v[84:87], v[208:211], v[12:15]
	v_mfma_f32_16x16x32_bf16 v[8:11], v[104:107], v[204:207], v[8:11]
	v_mfma_f32_16x16x32_bf16 v[8:11], v[108:111], v[208:211], v[8:11]
	v_mfma_f32_16x16x32_bf16 v[52:55], v[144:147], v[160:163], v[52:55]
	v_mfma_f32_16x16x32_bf16 v[52:55], v[148:151], v[164:167], v[52:55]
	v_mfma_f32_16x16x32_bf16 v[48:51], v[152:155], v[160:163], v[48:51]
	v_mfma_f32_16x16x32_bf16 v[48:51], v[156:159], v[164:167], v[48:51]
	v_mfma_f32_16x16x32_bf16 v[36:39], v[144:147], v[188:191], v[36:39]
	v_mfma_f32_16x16x32_bf16 v[36:39], v[148:151], v[192:195], v[36:39]
	v_mfma_f32_16x16x32_bf16 v[32:35], v[152:155], v[188:191], v[32:35]
	v_mfma_f32_16x16x32_bf16 v[32:35], v[156:159], v[192:195], v[32:35]
	v_mfma_f32_16x16x32_bf16 v[20:23], v[144:147], v[196:199], v[20:23]
	v_mfma_f32_16x16x32_bf16 v[20:23], v[148:151], v[200:203], v[20:23]
	v_mfma_f32_16x16x32_bf16 v[16:19], v[152:155], v[196:199], v[16:19]
	v_mfma_f32_16x16x32_bf16 v[16:19], v[156:159], v[200:203], v[16:19]
	v_mfma_f32_16x16x32_bf16 v[4:7], v[144:147], v[204:207], v[4:7]
	v_mfma_f32_16x16x32_bf16 v[4:7], v[148:151], v[208:211], v[4:7]
	v_mfma_f32_16x16x32_bf16 v[0:3], v[152:155], v[204:207], v[0:3]
	v_mfma_f32_16x16x32_bf16 v[0:3], v[156:159], v[208:211], v[0:3]
	s_barrier
	s_add_i32 s67, s67, 2
	s_add_u32 s57, s57, 0x80000
	s_addc_u32 s59, s59, 0
	s_add_u32 s10, s10, 0x400000
	s_addc_u32 s11, s11, 0
	s_cmpk_gt_u32 s67, 0x55
	s_cbranch_scc0 .LBB0_1154
	s_and_b64 vcc, exec, s[46:47]
	s_cbranch_vccz .LBB0_1157
	s_barrier
